# P0 stores write-through (sc0 sc1) so the P0->P1 barrier needs no L2 writeback; on top of per-XCD partition
# baseline (speedup 1.0000x reference)
.LBB0_18:
	s_waitcnt vmcnt(30)
	ds_write2_b32 v130, v34, v35 offset1:66
	s_waitcnt vmcnt(28)
	ds_write2_b32 v130, v36, v37 offset0:132 offset1:198
	s_waitcnt vmcnt(26)
	ds_write2_b32 v136, v38, v39 offset0:8 offset1:74
	s_waitcnt vmcnt(24)
	ds_write2_b32 v136, v40, v41 offset0:140 offset1:206
	s_waitcnt vmcnt(22)
	ds_write2_b32 v137, v42, v43 offset0:16 offset1:82
	s_waitcnt vmcnt(20)
	ds_write2_b32 v137, v44, v45 offset0:148 offset1:214
	s_waitcnt vmcnt(18)
	ds_write2_b32 v138, v46, v47 offset0:24 offset1:90
	s_waitcnt vmcnt(16)
	ds_write2_b32 v138, v48, v49 offset0:156 offset1:222
	s_waitcnt vmcnt(14)
	ds_write2_b32 v139, v50, v51 offset0:32 offset1:98
	s_waitcnt vmcnt(12)
	ds_write2_b32 v139, v52, v53 offset0:164 offset1:230
	s_waitcnt vmcnt(10)
	ds_write2_b32 v140, v54, v55 offset0:40 offset1:106
	s_waitcnt vmcnt(8)
	ds_write2_b32 v140, v56, v57 offset0:172 offset1:238
	s_waitcnt vmcnt(6)
	ds_write2_b32 v141, v58, v59 offset0:48 offset1:114
	s_waitcnt vmcnt(4)
	ds_write2_b32 v141, v60, v61 offset0:180 offset1:246
	s_waitcnt vmcnt(2)
	ds_write2_b32 v142, v64, v65 offset0:56 offset1:122
	s_waitcnt vmcnt(0)
	ds_write2_b32 v142, v62, v63 offset0:188 offset1:254
	s_waitcnt lgkmcnt(0)
	ds_read2_b32 v[38:39], v132 offset0:33 offset1:41
	ds_read2_b32 v[40:41], v132 offset1:8
	ds_read2_b32 v[42:43], v132 offset0:66 offset1:74
	ds_read2_b32 v[44:45], v132 offset0:99 offset1:107
	ds_read2_b32 v[46:47], v132 offset0:132 offset1:140
	ds_read2_b32 v[48:49], v132 offset0:165 offset1:173
	ds_read2_b32 v[50:51], v132 offset0:198 offset1:206
	ds_read2_b32 v[52:53], v132 offset0:231 offset1:239
	v_add_u32_e32 v56, s0, v131
	s_ashr_i32 s11, s10, 31
	v_ashrrev_i32_e32 v57, 31, v56
	v_lshl_add_u64 v[54:55], s[10:11], 1, v[32:33]
	v_lshlrev_b64 v[58:59], 11, v[56:57]
	s_waitcnt lgkmcnt(6)
	v_cvt_pk_bf16_f32 v34, v40, v38
	s_waitcnt lgkmcnt(4)
	v_cvt_pk_bf16_f32 v35, v42, v44
	s_waitcnt lgkmcnt(2)
	v_cvt_pk_bf16_f32 v36, v46, v48
	s_waitcnt lgkmcnt(0)
	v_cvt_pk_bf16_f32 v37, v50, v52
	v_lshl_add_u64 v[58:59], v[54:55], 0, v[58:59]
	v_add_u32_e32 v38, 8, v56
	global_store_dwordx4 v[58:59], v[34:37], off sc0 sc1
	s_nop 1
	v_cvt_pk_bf16_f32 v34, v41, v39
	v_ashrrev_i32_e32 v39, 31, v38
	v_cvt_pk_bf16_f32 v35, v43, v45
	v_cvt_pk_bf16_f32 v36, v47, v49
	v_cvt_pk_bf16_f32 v37, v51, v53
	v_lshlrev_b64 v[38:39], 11, v[38:39]
	ds_read2_b32 v[40:41], v132 offset0:49 offset1:57
	ds_read2_b32 v[42:43], v132 offset0:16 offset1:24
	ds_read2_b32 v[44:45], v132 offset0:82 offset1:90
	ds_read2_b32 v[46:47], v132 offset0:115 offset1:123
	ds_read2_b32 v[48:49], v132 offset0:148 offset1:156
	ds_read2_b32 v[50:51], v132 offset0:181 offset1:189
	ds_read2_b32 v[52:53], v132 offset0:214 offset1:222
	ds_read2_b32 v[58:59], v132 offset0:247 offset1:255
	v_lshl_add_u64 v[38:39], v[54:55], 0, v[38:39]
	global_store_dwordx4 v[38:39], v[34:37], off sc0 sc1
	v_add_u32_e32 v38, 16, v56
	v_ashrrev_i32_e32 v39, 31, v38
	v_lshlrev_b64 v[38:39], 11, v[38:39]
	s_waitcnt lgkmcnt(6)
	v_cvt_pk_bf16_f32 v34, v42, v40
	s_waitcnt lgkmcnt(4)
	v_cvt_pk_bf16_f32 v35, v44, v46
	s_waitcnt lgkmcnt(2)
	v_cvt_pk_bf16_f32 v36, v48, v50
	s_waitcnt lgkmcnt(0)
	v_cvt_pk_bf16_f32 v37, v52, v58
	v_lshl_add_u64 v[38:39], v[54:55], 0, v[38:39]
	global_store_dwordx4 v[38:39], v[34:37], off sc0 sc1
	v_add_u32_e32 v38, 24, v56
	v_ashrrev_i32_e32 v39, 31, v38
	v_lshlrev_b64 v[38:39], 11, v[38:39]
	v_cvt_pk_bf16_f32 v34, v43, v41
	v_cvt_pk_bf16_f32 v35, v45, v47
	v_cvt_pk_bf16_f32 v36, v49, v51
	v_cvt_pk_bf16_f32 v37, v53, v59
	v_lshl_add_u64 v[38:39], v[54:55], 0, v[38:39]
	global_store_dwordx4 v[38:39], v[34:37], off sc0 sc1
	s_waitcnt lgkmcnt(0)

.LBB0_20:
	s_cmpk_gt_i32 s21, 0xaff
	s_mov_b64 s[10:11], -1
	s_cbranch_scc0 .LBB0_50
	s_cmpk_gt_u32 s21, 0xbff
	s_cbranch_scc0 .LBB0_47
	s_cmpk_gt_u32 s21, 0xcff
	s_cbranch_scc0 .LBB0_44
	s_cmpk_gt_u32 s21, 0xeff
	s_cbranch_scc0 .LBB0_41
	s_cmpk_gt_u32 s21, 0x19ff
	s_cbranch_scc0 .LBB0_36
	s_and_b32 s22, s12, 0x3e0
	s_cmpk_gt_u32 s21, 0x1f7f
	s_cbranch_scc0 .LBB0_33
	s_cmpk_gt_u32 s21, 0x217f
	s_cbranch_scc0 .LBB0_28
	s_and_b32 s0, s16, 0x7fffffc0
	s_add_i32 s10, s0, 0xffffbd00
	v_or_b32_e32 v34, s10, v17
	v_or_b32_e32 v40, 2, v34
	v_or_b32_e32 v42, 4, v34
	v_or_b32_e32 v44, 6, v34
	v_or_b32_e32 v46, 8, v34
	v_or_b32_e32 v48, 10, v34
	v_or_b32_e32 v50, 12, v34
	v_or_b32_e32 v52, 14, v34
	s_lshl_b32 s0, s22, 2
	v_ashrrev_i32_e32 v35, 31, v34
	v_ashrrev_i32_e32 v41, 31, v40
	v_ashrrev_i32_e32 v43, 31, v42
	v_ashrrev_i32_e32 v45, 31, v44
	v_ashrrev_i32_e32 v47, 31, v46
	v_ashrrev_i32_e32 v49, 31, v48
	v_ashrrev_i32_e32 v51, 31, v50
	v_ashrrev_i32_e32 v53, 31, v52
	v_lshl_add_u64 v[36:37], v[2:3], 0, s[0:1]
	v_lshlrev_b64 v[38:39], 12, v[34:35]
	v_lshlrev_b64 v[40:41], 12, v[40:41]
	v_lshlrev_b64 v[42:43], 12, v[42:43]
	v_lshlrev_b64 v[44:45], 12, v[44:45]
	v_lshlrev_b64 v[46:47], 12, v[46:47]
	v_lshlrev_b64 v[48:49], 12, v[48:49]
	v_lshlrev_b64 v[50:51], 12, v[50:51]
	v_lshlrev_b64 v[52:53], 12, v[52:53]
	v_lshl_add_u64 v[38:39], v[36:37], 0, v[38:39]
	v_lshl_add_u64 v[40:41], v[36:37], 0, v[40:41]
	v_lshl_add_u64 v[42:43], v[36:37], 0, v[42:43]
	v_lshl_add_u64 v[44:45], v[36:37], 0, v[44:45]
	v_lshl_add_u64 v[46:47], v[36:37], 0, v[46:47]
	v_lshl_add_u64 v[48:49], v[36:37], 0, v[48:49]
	v_lshl_add_u64 v[50:51], v[36:37], 0, v[50:51]
	v_lshl_add_u64 v[52:53], v[36:37], 0, v[52:53]
	global_load_dword v54, v[38:39], off nt
	global_load_dword v55, v[40:41], off nt
	global_load_dword v56, v[42:43], off nt
	global_load_dword v57, v[44:45], off nt
	global_load_dword v58, v[46:47], off nt
	global_load_dword v59, v[48:49], off nt
	global_load_dword v60, v[50:51], off nt
	global_load_dword v61, v[52:53], off nt
	v_or_b32_e32 v38, 16, v34
	v_or_b32_e32 v40, 18, v34
	v_or_b32_e32 v42, 20, v34
	v_or_b32_e32 v44, 22, v34
	v_or_b32_e32 v46, 24, v34
	v_or_b32_e32 v48, 26, v34
	v_or_b32_e32 v50, 28, v34
	v_or_b32_e32 v52, 30, v34
	v_ashrrev_i32_e32 v39, 31, v38
	v_ashrrev_i32_e32 v41, 31, v40
	v_ashrrev_i32_e32 v43, 31, v42
	v_ashrrev_i32_e32 v45, 31, v44
	v_ashrrev_i32_e32 v47, 31, v46
	v_ashrrev_i32_e32 v49, 31, v48
	v_ashrrev_i32_e32 v51, 31, v50
	v_ashrrev_i32_e32 v53, 31, v52
	v_lshlrev_b64 v[38:39], 12, v[38:39]
	v_lshlrev_b64 v[40:41], 12, v[40:41]
	v_lshlrev_b64 v[42:43], 12, v[42:43]
	v_lshlrev_b64 v[44:45], 12, v[44:45]
	v_lshlrev_b64 v[46:47], 12, v[46:47]
	v_lshlrev_b64 v[48:49], 12, v[48:49]
	v_lshlrev_b64 v[50:51], 12, v[50:51]
	v_lshlrev_b64 v[52:53], 12, v[52:53]
	v_lshl_add_u64 v[38:39], v[36:37], 0, v[38:39]
	v_lshl_add_u64 v[40:41], v[36:37], 0, v[40:41]
	v_lshl_add_u64 v[42:43], v[36:37], 0, v[42:43]
	v_lshl_add_u64 v[44:45], v[36:37], 0, v[44:45]
	v_lshl_add_u64 v[46:47], v[36:37], 0, v[46:47]
	v_lshl_add_u64 v[48:49], v[36:37], 0, v[48:49]
	v_lshl_add_u64 v[50:51], v[36:37], 0, v[50:51]
	v_lshl_add_u64 v[52:53], v[36:37], 0, v[52:53]
	global_load_dword v62, v[38:39], off nt
	global_load_dword v63, v[40:41], off nt
	global_load_dword v64, v[42:43], off nt
	global_load_dword v65, v[44:45], off nt
	global_load_dword v66, v[46:47], off nt
	global_load_dword v67, v[48:49], off nt
	global_load_dword v68, v[50:51], off nt
	global_load_dword v69, v[52:53], off nt
	v_or_b32_e32 v38, 32, v34
	v_or_b32_e32 v40, 34, v34
	v_or_b32_e32 v42, 36, v34
	v_or_b32_e32 v44, 38, v34
	v_or_b32_e32 v46, 40, v34
	v_or_b32_e32 v48, 42, v34
	v_or_b32_e32 v50, 44, v34
	v_or_b32_e32 v52, 46, v34
	v_ashrrev_i32_e32 v39, 31, v38
	v_ashrrev_i32_e32 v41, 31, v40
	v_ashrrev_i32_e32 v43, 31, v42
	v_ashrrev_i32_e32 v45, 31, v44
	v_ashrrev_i32_e32 v47, 31, v46
	v_ashrrev_i32_e32 v49, 31, v48
	v_ashrrev_i32_e32 v51, 31, v50
	v_ashrrev_i32_e32 v53, 31, v52
	v_lshlrev_b64 v[38:39], 12, v[38:39]
	v_lshlrev_b64 v[40:41], 12, v[40:41]
	v_lshlrev_b64 v[42:43], 12, v[42:43]
	v_lshlrev_b64 v[44:45], 12, v[44:45]
	v_lshlrev_b64 v[46:47], 12, v[46:47]
	v_lshlrev_b64 v[48:49], 12, v[48:49]
	v_lshlrev_b64 v[50:51], 12, v[50:51]
	v_lshlrev_b64 v[52:53], 12, v[52:53]
	v_lshl_add_u64 v[38:39], v[36:37], 0, v[38:39]
	v_lshl_add_u64 v[40:41], v[36:37], 0, v[40:41]
	v_lshl_add_u64 v[42:43], v[36:37], 0, v[42:43]
	v_lshl_add_u64 v[44:45], v[36:37], 0, v[44:45]
	v_lshl_add_u64 v[46:47], v[36:37], 0, v[46:47]
	v_lshl_add_u64 v[48:49], v[36:37], 0, v[48:49]
	v_lshl_add_u64 v[50:51], v[36:37], 0, v[50:51]
	v_lshl_add_u64 v[52:53], v[36:37], 0, v[52:53]
	global_load_dword v70, v[38:39], off nt
	global_load_dword v71, v[40:41], off nt
	global_load_dword v72, v[42:43], off nt
	global_load_dword v73, v[44:45], off nt
	global_load_dword v74, v[46:47], off nt
	global_load_dword v75, v[48:49], off nt
	global_load_dword v76, v[50:51], off nt
	s_nop 0
	global_load_dword v52, v[52:53], off nt
	v_or_b32_e32 v38, 48, v34
	v_or_b32_e32 v40, 50, v34
	v_or_b32_e32 v42, 52, v34
	v_or_b32_e32 v44, 54, v34
	v_or_b32_e32 v46, 56, v34
	v_or_b32_e32 v48, 58, v34
	v_or_b32_e32 v50, 60, v34
	v_or_b32_e32 v34, 62, v34
	v_ashrrev_i32_e32 v39, 31, v38
	v_ashrrev_i32_e32 v41, 31, v40
	v_ashrrev_i32_e32 v43, 31, v42
	v_ashrrev_i32_e32 v35, 31, v34
	v_lshlrev_b64 v[38:39], 12, v[38:39]
	v_lshlrev_b64 v[40:41], 12, v[40:41]
	v_lshlrev_b64 v[42:43], 12, v[42:43]
	v_ashrrev_i32_e32 v45, 31, v44
	v_ashrrev_i32_e32 v47, 31, v46
	v_ashrrev_i32_e32 v49, 31, v48
	v_ashrrev_i32_e32 v51, 31, v50
	v_lshlrev_b64 v[34:35], 12, v[34:35]
	v_lshl_add_u64 v[38:39], v[36:37], 0, v[38:39]
	v_lshl_add_u64 v[40:41], v[36:37], 0, v[40:41]
	v_lshl_add_u64 v[42:43], v[36:37], 0, v[42:43]
	v_lshlrev_b64 v[44:45], 12, v[44:45]
	v_lshlrev_b64 v[46:47], 12, v[46:47]
	v_lshlrev_b64 v[48:49], 12, v[48:49]
	v_lshlrev_b64 v[50:51], 12, v[50:51]
	v_lshl_add_u64 v[34:35], v[36:37], 0, v[34:35]
	v_lshl_add_u64 v[44:45], v[36:37], 0, v[44:45]
	v_lshl_add_u64 v[46:47], v[36:37], 0, v[46:47]
	v_lshl_add_u64 v[48:49], v[36:37], 0, v[48:49]
	v_lshl_add_u64 v[50:51], v[36:37], 0, v[50:51]
	global_load_dword v36, v[38:39], off nt
	global_load_dword v37, v[40:41], off nt
	s_nop 0
	global_load_dword v38, v[42:43], off nt
	global_load_dword v39, v[44:45], off nt
	global_load_dword v40, v[46:47], off nt
	global_load_dword v41, v[48:49], off nt
	s_nop 0
	global_load_dword v42, v[50:51], off nt
	s_nop 0
	global_load_dword v34, v[34:35], off nt
	s_waitcnt vmcnt(30)
	ds_write2_b32 v130, v54, v55 offset1:66
	s_waitcnt vmcnt(28)
	ds_write2_b32 v130, v56, v57 offset0:132 offset1:198
	s_waitcnt vmcnt(26)
	ds_write2_b32 v136, v58, v59 offset0:8 offset1:74
	s_waitcnt vmcnt(24)
	ds_write2_b32 v136, v60, v61 offset0:140 offset1:206
	s_waitcnt vmcnt(22)
	ds_write2_b32 v137, v62, v63 offset0:16 offset1:82
	s_waitcnt vmcnt(20)
	ds_write2_b32 v137, v64, v65 offset0:148 offset1:214
	s_waitcnt vmcnt(18)
	ds_write2_b32 v138, v66, v67 offset0:24 offset1:90
	s_waitcnt vmcnt(16)
	ds_write2_b32 v138, v68, v69 offset0:156 offset1:222
	s_waitcnt vmcnt(14)
	ds_write2_b32 v139, v70, v71 offset0:32 offset1:98
	s_waitcnt vmcnt(12)
	ds_write2_b32 v139, v72, v73 offset0:164 offset1:230
	s_waitcnt vmcnt(10)
	ds_write2_b32 v140, v74, v75 offset0:40 offset1:106
	s_waitcnt vmcnt(8)
	ds_write2_b32 v140, v76, v52 offset0:172 offset1:238
	s_waitcnt vmcnt(6)
	ds_write2_b32 v141, v36, v37 offset0:48 offset1:114
	s_waitcnt vmcnt(4)
	ds_write2_b32 v141, v38, v39 offset0:180 offset1:246
	s_waitcnt vmcnt(2)
	ds_write2_b32 v142, v40, v41 offset0:56 offset1:122
	s_waitcnt vmcnt(0)
	ds_write2_b32 v142, v42, v34 offset0:188 offset1:254
	s_waitcnt lgkmcnt(0)
	ds_read2_b32 v[38:39], v132 offset0:33 offset1:41
	ds_read2_b32 v[40:41], v132 offset1:8
	ds_read2_b32 v[42:43], v132 offset0:66 offset1:74
	ds_read2_b32 v[44:45], v132 offset0:99 offset1:107
	ds_read2_b32 v[46:47], v132 offset0:132 offset1:140
	ds_read2_b32 v[48:49], v132 offset0:165 offset1:173
	ds_read2_b32 v[50:51], v132 offset0:198 offset1:206
	ds_read2_b32 v[52:53], v132 offset0:231 offset1:239
	s_mov_b32 s11, s1
	s_waitcnt lgkmcnt(6)
	v_cvt_pk_bf16_f32 v34, v40, v38
	v_or_b32_e32 v38, s22, v131
	v_lshl_add_u64 v[54:55], s[10:11], 1, v[4:5]
	v_lshlrev_b32_e32 v56, 9, v38
	v_mov_b32_e32 v57, v1
	s_waitcnt lgkmcnt(4)
	v_cvt_pk_bf16_f32 v35, v42, v44
	s_waitcnt lgkmcnt(2)
	v_cvt_pk_bf16_f32 v36, v46, v48
	s_waitcnt lgkmcnt(0)
	v_cvt_pk_bf16_f32 v37, v50, v52
	v_lshl_add_u64 v[56:57], v[54:55], 0, v[56:57]
	global_store_dwordx4 v[56:57], v[34:37], off sc0 sc1
	v_or_b32_e32 v38, s22, v133
	v_lshlrev_b32_e32 v38, 9, v38
	v_cvt_pk_bf16_f32 v34, v41, v39
	v_cvt_pk_bf16_f32 v35, v43, v45
	v_cvt_pk_bf16_f32 v36, v47, v49
	v_cvt_pk_bf16_f32 v37, v51, v53
	ds_read2_b32 v[40:41], v132 offset0:49 offset1:57
	ds_read2_b32 v[42:43], v132 offset0:16 offset1:24
	ds_read2_b32 v[44:45], v132 offset0:82 offset1:90
	ds_read2_b32 v[46:47], v132 offset0:115 offset1:123
	ds_read2_b32 v[48:49], v132 offset0:148 offset1:156
	ds_read2_b32 v[50:51], v132 offset0:181 offset1:189
	ds_read2_b32 v[52:53], v132 offset0:214 offset1:222
	ds_read2_b32 v[56:57], v132 offset0:247 offset1:255
	v_mov_b32_e32 v39, v1
	v_lshl_add_u64 v[38:39], v[54:55], 0, v[38:39]
	global_store_dwordx4 v[38:39], v[34:37], off sc0 sc1
	v_or_b32_e32 v38, s22, v134
	v_lshlrev_b32_e32 v38, 9, v38
	v_mov_b32_e32 v39, v1
	s_waitcnt lgkmcnt(6)
	v_cvt_pk_bf16_f32 v34, v42, v40
	s_waitcnt lgkmcnt(4)
	v_cvt_pk_bf16_f32 v35, v44, v46
	s_waitcnt lgkmcnt(2)
	v_cvt_pk_bf16_f32 v36, v48, v50
	s_waitcnt lgkmcnt(0)
	v_cvt_pk_bf16_f32 v37, v52, v56
	v_lshl_add_u64 v[38:39], v[54:55], 0, v[38:39]
	global_store_dwordx4 v[38:39], v[34:37], off sc0 sc1
	v_or_b32_e32 v38, s22, v135
	v_lshlrev_b32_e32 v38, 9, v38
	v_mov_b32_e32 v39, v1
	v_cvt_pk_bf16_f32 v34, v43, v41
	v_cvt_pk_bf16_f32 v35, v45, v47
	v_cvt_pk_bf16_f32 v36, v49, v51
	v_cvt_pk_bf16_f32 v37, v53, v57
	v_lshl_add_u64 v[38:39], v[54:55], 0, v[38:39]
	global_store_dwordx4 v[38:39], v[34:37], off sc0 sc1
	s_waitcnt lgkmcnt(0)
	s_mov_b64 s[10:11], 0

.LBB0_31:
	s_waitcnt vmcnt(30)
	ds_write2_b32 v130, v34, v35 offset1:66
	s_waitcnt vmcnt(28)
	ds_write2_b32 v130, v36, v37 offset0:132 offset1:198
	s_waitcnt vmcnt(26)
	ds_write2_b32 v136, v38, v39 offset0:8 offset1:74
	s_waitcnt vmcnt(24)
	ds_write2_b32 v136, v40, v41 offset0:140 offset1:206
	s_waitcnt vmcnt(22)
	ds_write2_b32 v137, v42, v43 offset0:16 offset1:82
	s_waitcnt vmcnt(20)
	ds_write2_b32 v137, v44, v45 offset0:148 offset1:214
	s_waitcnt vmcnt(18)
	ds_write2_b32 v138, v46, v47 offset0:24 offset1:90
	s_waitcnt vmcnt(16)
	ds_write2_b32 v138, v48, v49 offset0:156 offset1:222
	s_waitcnt vmcnt(14)
	ds_write2_b32 v139, v50, v51 offset0:32 offset1:98
	s_waitcnt vmcnt(12)
	ds_write2_b32 v139, v52, v53 offset0:164 offset1:230
	s_waitcnt vmcnt(10)
	ds_write2_b32 v140, v54, v55 offset0:40 offset1:106
	s_waitcnt vmcnt(8)
	ds_write2_b32 v140, v56, v57 offset0:172 offset1:238
	s_waitcnt vmcnt(6)
	ds_write2_b32 v141, v58, v59 offset0:48 offset1:114
	s_waitcnt vmcnt(4)
	ds_write2_b32 v141, v60, v61 offset0:180 offset1:246
	s_waitcnt vmcnt(2)
	ds_write2_b32 v142, v64, v65 offset0:56 offset1:122
	s_waitcnt vmcnt(0)
	ds_write2_b32 v142, v62, v63 offset0:188 offset1:254
	s_waitcnt lgkmcnt(0)
	ds_read2_b32 v[38:39], v132 offset0:33 offset1:41
	ds_read2_b32 v[40:41], v132 offset1:8
	ds_read2_b32 v[42:43], v132 offset0:66 offset1:74
	ds_read2_b32 v[44:45], v132 offset0:99 offset1:107
	ds_read2_b32 v[46:47], v132 offset0:132 offset1:140
	ds_read2_b32 v[48:49], v132 offset0:165 offset1:173
	ds_read2_b32 v[50:51], v132 offset0:198 offset1:206
	ds_read2_b32 v[52:53], v132 offset0:231 offset1:239
	s_mov_b32 s11, s1
	s_waitcnt lgkmcnt(6)
	v_cvt_pk_bf16_f32 v34, v40, v38
	v_or_b32_e32 v38, s22, v131
	v_lshl_add_u64 v[54:55], s[10:11], 1, v[8:9]
	v_lshlrev_b32_e32 v56, 11, v38
	v_mov_b32_e32 v57, v1
	s_waitcnt lgkmcnt(4)
	v_cvt_pk_bf16_f32 v35, v42, v44
	s_waitcnt lgkmcnt(2)
	v_cvt_pk_bf16_f32 v36, v46, v48
	s_waitcnt lgkmcnt(0)
	v_cvt_pk_bf16_f32 v37, v50, v52
	v_lshl_add_u64 v[56:57], v[54:55], 0, v[56:57]
	global_store_dwordx4 v[56:57], v[34:37], off sc0 sc1
	v_or_b32_e32 v38, s22, v133
	v_lshlrev_b32_e32 v38, 11, v38
	v_cvt_pk_bf16_f32 v34, v41, v39
	v_cvt_pk_bf16_f32 v35, v43, v45
	v_cvt_pk_bf16_f32 v36, v47, v49
	v_cvt_pk_bf16_f32 v37, v51, v53
	ds_read2_b32 v[40:41], v132 offset0:49 offset1:57
	ds_read2_b32 v[42:43], v132 offset0:16 offset1:24
	ds_read2_b32 v[44:45], v132 offset0:82 offset1:90
	ds_read2_b32 v[46:47], v132 offset0:115 offset1:123
	ds_read2_b32 v[48:49], v132 offset0:148 offset1:156
	ds_read2_b32 v[50:51], v132 offset0:181 offset1:189
	ds_read2_b32 v[52:53], v132 offset0:214 offset1:222
	ds_read2_b32 v[56:57], v132 offset0:247 offset1:255
	v_mov_b32_e32 v39, v1
	v_lshl_add_u64 v[38:39], v[54:55], 0, v[38:39]
	global_store_dwordx4 v[38:39], v[34:37], off sc0 sc1
	v_or_b32_e32 v38, s22, v134
	v_lshlrev_b32_e32 v38, 11, v38
	v_mov_b32_e32 v39, v1
	s_waitcnt lgkmcnt(6)
	v_cvt_pk_bf16_f32 v34, v42, v40
	s_waitcnt lgkmcnt(4)
	v_cvt_pk_bf16_f32 v35, v44, v46
	s_waitcnt lgkmcnt(2)
	v_cvt_pk_bf16_f32 v36, v48, v50
	s_waitcnt lgkmcnt(0)
	v_cvt_pk_bf16_f32 v37, v52, v56
	v_lshl_add_u64 v[38:39], v[54:55], 0, v[38:39]
	global_store_dwordx4 v[38:39], v[34:37], off sc0 sc1
	v_or_b32_e32 v38, s22, v135
	v_lshlrev_b32_e32 v38, 11, v38
	v_mov_b32_e32 v39, v1
	v_cvt_pk_bf16_f32 v34, v43, v41
	v_cvt_pk_bf16_f32 v35, v45, v47
	v_cvt_pk_bf16_f32 v36, v49, v51
	v_cvt_pk_bf16_f32 v37, v53, v57
	v_lshl_add_u64 v[38:39], v[54:55], 0, v[38:39]
	global_store_dwordx4 v[38:39], v[34:37], off sc0 sc1
	s_waitcnt lgkmcnt(0)

.LBB0_33:
	s_andn2_b64 vcc, exec, s[10:11]
	s_cbranch_vccnz .LBB0_35
	s_and_b32 s0, s16, 0x3fc0
	s_add_i32 s10, s0, 0xffffcc00
	v_or_b32_e32 v34, s10, v17
	v_or_b32_e32 v40, 2, v34
	v_or_b32_e32 v42, 4, v34
	v_or_b32_e32 v44, 6, v34
	v_or_b32_e32 v46, 8, v34
	v_or_b32_e32 v48, 10, v34
	v_or_b32_e32 v50, 12, v34
	v_or_b32_e32 v52, 14, v34
	s_lshl_b32 s0, s22, 2
	v_ashrrev_i32_e32 v35, 31, v34
	v_ashrrev_i32_e32 v41, 31, v40
	v_ashrrev_i32_e32 v43, 31, v42
	v_ashrrev_i32_e32 v45, 31, v44
	v_ashrrev_i32_e32 v47, 31, v46
	v_ashrrev_i32_e32 v49, 31, v48
	v_ashrrev_i32_e32 v51, 31, v50
	v_ashrrev_i32_e32 v53, 31, v52
	v_lshl_add_u64 v[36:37], v[10:11], 0, s[0:1]
	v_lshlrev_b64 v[38:39], 12, v[34:35]
	v_lshlrev_b64 v[40:41], 12, v[40:41]
	v_lshlrev_b64 v[42:43], 12, v[42:43]
	v_lshlrev_b64 v[44:45], 12, v[44:45]
	v_lshlrev_b64 v[46:47], 12, v[46:47]
	v_lshlrev_b64 v[48:49], 12, v[48:49]
	v_lshlrev_b64 v[50:51], 12, v[50:51]
	v_lshlrev_b64 v[52:53], 12, v[52:53]
	v_lshl_add_u64 v[38:39], v[36:37], 0, v[38:39]
	v_lshl_add_u64 v[40:41], v[36:37], 0, v[40:41]
	v_lshl_add_u64 v[42:43], v[36:37], 0, v[42:43]
	v_lshl_add_u64 v[44:45], v[36:37], 0, v[44:45]
	v_lshl_add_u64 v[46:47], v[36:37], 0, v[46:47]
	v_lshl_add_u64 v[48:49], v[36:37], 0, v[48:49]
	v_lshl_add_u64 v[50:51], v[36:37], 0, v[50:51]
	v_lshl_add_u64 v[52:53], v[36:37], 0, v[52:53]
	global_load_dword v54, v[38:39], off nt
	global_load_dword v55, v[40:41], off nt
	global_load_dword v56, v[42:43], off nt
	global_load_dword v57, v[44:45], off nt
	global_load_dword v58, v[46:47], off nt
	global_load_dword v59, v[48:49], off nt
	global_load_dword v60, v[50:51], off nt
	global_load_dword v61, v[52:53], off nt
	v_or_b32_e32 v38, 16, v34
	v_or_b32_e32 v40, 18, v34
	v_or_b32_e32 v42, 20, v34
	v_or_b32_e32 v44, 22, v34
	v_or_b32_e32 v46, 24, v34
	v_or_b32_e32 v48, 26, v34
	v_or_b32_e32 v50, 28, v34
	v_or_b32_e32 v52, 30, v34
	v_ashrrev_i32_e32 v39, 31, v38
	v_ashrrev_i32_e32 v41, 31, v40
	v_ashrrev_i32_e32 v43, 31, v42
	v_ashrrev_i32_e32 v45, 31, v44
	v_ashrrev_i32_e32 v47, 31, v46
	v_ashrrev_i32_e32 v49, 31, v48
	v_ashrrev_i32_e32 v51, 31, v50
	v_ashrrev_i32_e32 v53, 31, v52
	v_lshlrev_b64 v[38:39], 12, v[38:39]
	v_lshlrev_b64 v[40:41], 12, v[40:41]
	v_lshlrev_b64 v[42:43], 12, v[42:43]
	v_lshlrev_b64 v[44:45], 12, v[44:45]
	v_lshlrev_b64 v[46:47], 12, v[46:47]
	v_lshlrev_b64 v[48:49], 12, v[48:49]
	v_lshlrev_b64 v[50:51], 12, v[50:51]
	v_lshlrev_b64 v[52:53], 12, v[52:53]
	v_lshl_add_u64 v[38:39], v[36:37], 0, v[38:39]
	v_lshl_add_u64 v[40:41], v[36:37], 0, v[40:41]
	v_lshl_add_u64 v[42:43], v[36:37], 0, v[42:43]
	v_lshl_add_u64 v[44:45], v[36:37], 0, v[44:45]
	v_lshl_add_u64 v[46:47], v[36:37], 0, v[46:47]
	v_lshl_add_u64 v[48:49], v[36:37], 0, v[48:49]
	v_lshl_add_u64 v[50:51], v[36:37], 0, v[50:51]
	v_lshl_add_u64 v[52:53], v[36:37], 0, v[52:53]
	global_load_dword v62, v[38:39], off nt
	global_load_dword v63, v[40:41], off nt
	global_load_dword v64, v[42:43], off nt
	global_load_dword v65, v[44:45], off nt
	global_load_dword v66, v[46:47], off nt
	global_load_dword v67, v[48:49], off nt
	global_load_dword v68, v[50:51], off nt
	global_load_dword v69, v[52:53], off nt
	v_or_b32_e32 v38, 32, v34
	v_or_b32_e32 v40, 34, v34
	v_or_b32_e32 v42, 36, v34
	v_or_b32_e32 v44, 38, v34
	v_or_b32_e32 v46, 40, v34
	v_or_b32_e32 v48, 42, v34
	v_or_b32_e32 v50, 44, v34
	v_or_b32_e32 v52, 46, v34
	v_ashrrev_i32_e32 v39, 31, v38
	v_ashrrev_i32_e32 v41, 31, v40
	v_ashrrev_i32_e32 v43, 31, v42
	v_ashrrev_i32_e32 v45, 31, v44
	v_ashrrev_i32_e32 v47, 31, v46
	v_ashrrev_i32_e32 v49, 31, v48
	v_ashrrev_i32_e32 v51, 31, v50
	v_ashrrev_i32_e32 v53, 31, v52
	v_lshlrev_b64 v[38:39], 12, v[38:39]
	v_lshlrev_b64 v[40:41], 12, v[40:41]
	v_lshlrev_b64 v[42:43], 12, v[42:43]
	v_lshlrev_b64 v[44:45], 12, v[44:45]
	v_lshlrev_b64 v[46:47], 12, v[46:47]
	v_lshlrev_b64 v[48:49], 12, v[48:49]
	v_lshlrev_b64 v[50:51], 12, v[50:51]
	v_lshlrev_b64 v[52:53], 12, v[52:53]
	v_lshl_add_u64 v[38:39], v[36:37], 0, v[38:39]
	v_lshl_add_u64 v[40:41], v[36:37], 0, v[40:41]
	v_lshl_add_u64 v[42:43], v[36:37], 0, v[42:43]
	v_lshl_add_u64 v[44:45], v[36:37], 0, v[44:45]
	v_lshl_add_u64 v[46:47], v[36:37], 0, v[46:47]
	v_lshl_add_u64 v[48:49], v[36:37], 0, v[48:49]
	v_lshl_add_u64 v[50:51], v[36:37], 0, v[50:51]
	v_lshl_add_u64 v[52:53], v[36:37], 0, v[52:53]
	global_load_dword v70, v[38:39], off nt
	global_load_dword v71, v[40:41], off nt
	global_load_dword v72, v[42:43], off nt
	global_load_dword v73, v[44:45], off nt
	global_load_dword v74, v[46:47], off nt
	global_load_dword v75, v[48:49], off nt
	global_load_dword v76, v[50:51], off nt
	s_nop 0
	global_load_dword v52, v[52:53], off nt
	v_or_b32_e32 v38, 48, v34
	v_or_b32_e32 v40, 50, v34
	v_or_b32_e32 v42, 52, v34
	v_or_b32_e32 v44, 54, v34
	v_or_b32_e32 v46, 56, v34
	v_or_b32_e32 v48, 58, v34
	v_or_b32_e32 v50, 60, v34
	v_or_b32_e32 v34, 62, v34
	v_ashrrev_i32_e32 v39, 31, v38
	v_ashrrev_i32_e32 v41, 31, v40
	v_ashrrev_i32_e32 v43, 31, v42
	v_ashrrev_i32_e32 v35, 31, v34
	v_lshlrev_b64 v[38:39], 12, v[38:39]
	v_lshlrev_b64 v[40:41], 12, v[40:41]
	v_lshlrev_b64 v[42:43], 12, v[42:43]
	v_ashrrev_i32_e32 v45, 31, v44
	v_ashrrev_i32_e32 v47, 31, v46
	v_ashrrev_i32_e32 v49, 31, v48
	v_ashrrev_i32_e32 v51, 31, v50
	v_lshlrev_b64 v[34:35], 12, v[34:35]
	v_lshl_add_u64 v[38:39], v[36:37], 0, v[38:39]
	v_lshl_add_u64 v[40:41], v[36:37], 0, v[40:41]
	v_lshl_add_u64 v[42:43], v[36:37], 0, v[42:43]
	v_lshlrev_b64 v[44:45], 12, v[44:45]
	v_lshlrev_b64 v[46:47], 12, v[46:47]
	v_lshlrev_b64 v[48:49], 12, v[48:49]
	v_lshlrev_b64 v[50:51], 12, v[50:51]
	v_lshl_add_u64 v[34:35], v[36:37], 0, v[34:35]
	v_lshl_add_u64 v[44:45], v[36:37], 0, v[44:45]
	v_lshl_add_u64 v[46:47], v[36:37], 0, v[46:47]
	v_lshl_add_u64 v[48:49], v[36:37], 0, v[48:49]
	v_lshl_add_u64 v[50:51], v[36:37], 0, v[50:51]
	global_load_dword v36, v[38:39], off nt
	global_load_dword v37, v[40:41], off nt
	s_nop 0
	global_load_dword v38, v[42:43], off nt
	global_load_dword v39, v[44:45], off nt
	global_load_dword v40, v[46:47], off nt
	global_load_dword v41, v[48:49], off nt
	s_nop 0
	global_load_dword v42, v[50:51], off nt
	s_nop 0
	global_load_dword v34, v[34:35], off nt
	s_waitcnt vmcnt(30)
	ds_write2_b32 v130, v54, v55 offset1:66
	s_waitcnt vmcnt(28)
	ds_write2_b32 v130, v56, v57 offset0:132 offset1:198
	s_waitcnt vmcnt(26)
	ds_write2_b32 v136, v58, v59 offset0:8 offset1:74
	s_waitcnt vmcnt(24)
	ds_write2_b32 v136, v60, v61 offset0:140 offset1:206
	s_waitcnt vmcnt(22)
	ds_write2_b32 v137, v62, v63 offset0:16 offset1:82
	s_waitcnt vmcnt(20)
	ds_write2_b32 v137, v64, v65 offset0:148 offset1:214
	s_waitcnt vmcnt(18)
	ds_write2_b32 v138, v66, v67 offset0:24 offset1:90
	s_waitcnt vmcnt(16)
	ds_write2_b32 v138, v68, v69 offset0:156 offset1:222
	s_waitcnt vmcnt(14)
	ds_write2_b32 v139, v70, v71 offset0:32 offset1:98
	s_waitcnt vmcnt(12)
	ds_write2_b32 v139, v72, v73 offset0:164 offset1:230
	s_waitcnt vmcnt(10)
	ds_write2_b32 v140, v74, v75 offset0:40 offset1:106
	s_waitcnt vmcnt(8)
	ds_write2_b32 v140, v76, v52 offset0:172 offset1:238
	s_waitcnt vmcnt(6)
	ds_write2_b32 v141, v36, v37 offset0:48 offset1:114
	s_waitcnt vmcnt(4)
	ds_write2_b32 v141, v38, v39 offset0:180 offset1:246
	s_waitcnt vmcnt(2)
	ds_write2_b32 v142, v40, v41 offset0:56 offset1:122
	s_waitcnt vmcnt(0)
	ds_write2_b32 v142, v42, v34 offset0:188 offset1:254
	s_waitcnt lgkmcnt(0)
	ds_read2_b32 v[38:39], v132 offset0:33 offset1:41
	ds_read2_b32 v[40:41], v132 offset1:8
	ds_read2_b32 v[42:43], v132 offset0:66 offset1:74
	ds_read2_b32 v[44:45], v132 offset0:99 offset1:107
	ds_read2_b32 v[46:47], v132 offset0:132 offset1:140
	ds_read2_b32 v[48:49], v132 offset0:165 offset1:173
	ds_read2_b32 v[50:51], v132 offset0:198 offset1:206
	ds_read2_b32 v[52:53], v132 offset0:231 offset1:239
	s_mov_b32 s11, s1
	s_waitcnt lgkmcnt(6)
	v_cvt_pk_bf16_f32 v34, v40, v38
	v_or_b32_e32 v38, s22, v131
	v_lshl_add_u64 v[54:55], s[10:11], 1, v[12:13]
	v_mul_u32_u24_e32 v56, 0x1600, v38
	v_mov_b32_e32 v57, v1
	s_waitcnt lgkmcnt(4)
	v_cvt_pk_bf16_f32 v35, v42, v44
	s_waitcnt lgkmcnt(2)
	v_cvt_pk_bf16_f32 v36, v46, v48
	s_waitcnt lgkmcnt(0)
	v_cvt_pk_bf16_f32 v37, v50, v52
	v_lshl_add_u64 v[56:57], v[54:55], 0, v[56:57]
	global_store_dwordx4 v[56:57], v[34:37], off sc0 sc1
	v_or_b32_e32 v38, s22, v133
	v_mul_u32_u24_e32 v38, 0x1600, v38
	v_cvt_pk_bf16_f32 v34, v41, v39
	v_cvt_pk_bf16_f32 v35, v43, v45
	v_cvt_pk_bf16_f32 v36, v47, v49
	v_cvt_pk_bf16_f32 v37, v51, v53
	ds_read2_b32 v[40:41], v132 offset0:16 offset1:24
	ds_read2_b32 v[42:43], v132 offset0:49 offset1:57
	ds_read2_b32 v[44:45], v132 offset0:82 offset1:90
	ds_read2_b32 v[46:47], v132 offset0:115 offset1:123
	ds_read2_b32 v[48:49], v132 offset0:148 offset1:156
	ds_read2_b32 v[50:51], v132 offset0:181 offset1:189
	ds_read2_b32 v[52:53], v132 offset0:214 offset1:222
	ds_read2_b32 v[56:57], v132 offset0:247 offset1:255
	v_mov_b32_e32 v39, v1
	v_lshl_add_u64 v[38:39], v[54:55], 0, v[38:39]
	global_store_dwordx4 v[38:39], v[34:37], off sc0 sc1
	v_or_b32_e32 v38, s22, v134
	v_mul_u32_u24_e32 v38, 0x1600, v38
	v_mov_b32_e32 v39, v1
	s_waitcnt lgkmcnt(6)
	v_cvt_pk_bf16_f32 v34, v40, v42
	s_waitcnt lgkmcnt(4)
	v_cvt_pk_bf16_f32 v35, v44, v46
	s_waitcnt lgkmcnt(2)
	v_cvt_pk_bf16_f32 v36, v48, v50
	s_waitcnt lgkmcnt(0)
	v_cvt_pk_bf16_f32 v37, v52, v56
	v_lshl_add_u64 v[38:39], v[54:55], 0, v[38:39]
	global_store_dwordx4 v[38:39], v[34:37], off sc0 sc1
	v_or_b32_e32 v38, s22, v135
	v_mul_u32_u24_e32 v38, 0x1600, v38
	v_mov_b32_e32 v39, v1
	v_cvt_pk_bf16_f32 v34, v41, v43
	v_cvt_pk_bf16_f32 v35, v45, v47
	v_cvt_pk_bf16_f32 v36, v49, v51
	v_cvt_pk_bf16_f32 v37, v53, v57
	v_lshl_add_u64 v[38:39], v[54:55], 0, v[38:39]
	global_store_dwordx4 v[38:39], v[34:37], off sc0 sc1
	s_waitcnt lgkmcnt(0)

.LBB0_39:
	s_waitcnt vmcnt(30)
	ds_write2_b32 v130, v34, v35 offset1:66
	s_waitcnt vmcnt(28)
	ds_write2_b32 v130, v36, v37 offset0:132 offset1:198
	s_waitcnt vmcnt(26)
	ds_write2_b32 v136, v38, v39 offset0:8 offset1:74
	s_waitcnt vmcnt(24)
	ds_write2_b32 v136, v40, v41 offset0:140 offset1:206
	s_waitcnt vmcnt(22)
	ds_write2_b32 v137, v42, v43 offset0:16 offset1:82
	s_waitcnt vmcnt(20)
	ds_write2_b32 v137, v44, v45 offset0:148 offset1:214
	s_waitcnt vmcnt(18)
	ds_write2_b32 v138, v46, v47 offset0:24 offset1:90
	s_waitcnt vmcnt(16)
	ds_write2_b32 v138, v48, v49 offset0:156 offset1:222
	s_waitcnt vmcnt(14)
	ds_write2_b32 v139, v50, v51 offset0:32 offset1:98
	s_waitcnt vmcnt(12)
	ds_write2_b32 v139, v52, v53 offset0:164 offset1:230
	s_waitcnt vmcnt(10)
	ds_write2_b32 v140, v54, v55 offset0:40 offset1:106
	s_waitcnt vmcnt(8)
	ds_write2_b32 v140, v56, v57 offset0:172 offset1:238
	s_waitcnt vmcnt(6)
	ds_write2_b32 v141, v58, v59 offset0:48 offset1:114
	s_waitcnt vmcnt(4)
	ds_write2_b32 v141, v60, v61 offset0:180 offset1:246
	s_waitcnt vmcnt(2)
	ds_write2_b32 v142, v64, v65 offset0:56 offset1:122
	s_waitcnt vmcnt(0)
	ds_write2_b32 v142, v62, v63 offset0:188 offset1:254
	s_waitcnt lgkmcnt(0)
	ds_read2_b32 v[38:39], v132 offset0:33 offset1:41
	ds_read2_b32 v[40:41], v132 offset1:8
	ds_read2_b32 v[42:43], v132 offset0:66 offset1:74
	ds_read2_b32 v[44:45], v132 offset0:99 offset1:107
	ds_read2_b32 v[46:47], v132 offset0:132 offset1:140
	ds_read2_b32 v[48:49], v132 offset0:165 offset1:173
	ds_read2_b32 v[50:51], v132 offset0:198 offset1:206
	ds_read2_b32 v[52:53], v132 offset0:231 offset1:239
	s_and_b32 s0, 0xffff, s0
	s_lshl_b32 s0, s0, 1
	s_waitcnt lgkmcnt(6)
	v_cvt_pk_bf16_f32 v34, v40, v38
	v_or_b32_e32 v38, s10, v131
	v_lshl_add_u64 v[54:55], v[14:15], 0, s[0:1]
	v_lshlrev_b32_e32 v56, 11, v38
	v_mov_b32_e32 v57, v1
	s_waitcnt lgkmcnt(4)
	v_cvt_pk_bf16_f32 v35, v42, v44
	s_waitcnt lgkmcnt(2)
	v_cvt_pk_bf16_f32 v36, v46, v48
	s_waitcnt lgkmcnt(0)
	v_cvt_pk_bf16_f32 v37, v50, v52
	v_lshl_add_u64 v[56:57], v[54:55], 0, v[56:57]
	global_store_dwordx4 v[56:57], v[34:37], off sc0 sc1
	v_or_b32_e32 v38, s10, v133
	v_lshlrev_b32_e32 v38, 11, v38
	v_cvt_pk_bf16_f32 v34, v41, v39
	v_cvt_pk_bf16_f32 v35, v43, v45
	v_cvt_pk_bf16_f32 v36, v47, v49
	v_cvt_pk_bf16_f32 v37, v51, v53
	ds_read2_b32 v[40:41], v132 offset0:49 offset1:57
	ds_read2_b32 v[42:43], v132 offset0:16 offset1:24
	ds_read2_b32 v[44:45], v132 offset0:82 offset1:90
	ds_read2_b32 v[46:47], v132 offset0:115 offset1:123
	ds_read2_b32 v[48:49], v132 offset0:148 offset1:156
	ds_read2_b32 v[50:51], v132 offset0:181 offset1:189
	ds_read2_b32 v[52:53], v132 offset0:214 offset1:222
	ds_read2_b32 v[56:57], v132 offset0:247 offset1:255
	v_mov_b32_e32 v39, v1
	v_lshl_add_u64 v[38:39], v[54:55], 0, v[38:39]
	global_store_dwordx4 v[38:39], v[34:37], off sc0 sc1
	v_or_b32_e32 v38, s10, v134
	v_lshlrev_b32_e32 v38, 11, v38
	v_mov_b32_e32 v39, v1
	s_waitcnt lgkmcnt(6)
	v_cvt_pk_bf16_f32 v34, v42, v40
	s_waitcnt lgkmcnt(4)
	v_cvt_pk_bf16_f32 v35, v44, v46
	s_waitcnt lgkmcnt(2)
	v_cvt_pk_bf16_f32 v36, v48, v50
	s_waitcnt lgkmcnt(0)
	v_cvt_pk_bf16_f32 v37, v52, v56
	v_lshl_add_u64 v[38:39], v[54:55], 0, v[38:39]
	global_store_dwordx4 v[38:39], v[34:37], off sc0 sc1
	v_or_b32_e32 v38, s10, v135
	v_lshlrev_b32_e32 v38, 11, v38
	v_mov_b32_e32 v39, v1
	v_cvt_pk_bf16_f32 v34, v43, v41
	v_cvt_pk_bf16_f32 v35, v45, v47
	v_cvt_pk_bf16_f32 v36, v49, v51
	v_cvt_pk_bf16_f32 v37, v53, v57
	v_lshl_add_u64 v[38:39], v[54:55], 0, v[38:39]
	global_store_dwordx4 v[38:39], v[34:37], off sc0 sc1
	s_waitcnt lgkmcnt(0)

.LBB0_41:
	s_andn2_b64 vcc, exec, s[10:11]
	s_cbranch_vccnz .LBB0_43
	s_and_b32 s0, s16, 0x1fc0
	s_add_i32 s10, s0, 0xffffe600
	s_and_b32 s22, s12, 0x3e0
	v_or_b32_e32 v34, s10, v17
	s_lshl_b32 s0, s22, 2
	v_mov_b32_e32 v35, v1
	v_or_b32_e32 v40, 2, v34
	v_mov_b32_e32 v41, v1
	v_or_b32_e32 v42, 4, v34
	v_mov_b32_e32 v43, v1
	v_or_b32_e32 v44, 6, v34
	v_mov_b32_e32 v45, v1
	v_or_b32_e32 v46, 8, v34
	v_mov_b32_e32 v47, v1
	v_or_b32_e32 v48, 10, v34
	v_mov_b32_e32 v49, v1
	v_or_b32_e32 v50, 12, v34
	v_mov_b32_e32 v51, v1
	v_or_b32_e32 v52, 14, v34
	v_mov_b32_e32 v53, v1
	v_lshl_add_u64 v[36:37], v[18:19], 0, s[0:1]
	v_lshlrev_b64 v[38:39], 12, v[34:35]
	v_lshlrev_b64 v[40:41], 12, v[40:41]
	v_lshlrev_b64 v[42:43], 12, v[42:43]
	v_lshlrev_b64 v[44:45], 12, v[44:45]
	v_lshlrev_b64 v[46:47], 12, v[46:47]
	v_lshlrev_b64 v[48:49], 12, v[48:49]
	v_lshlrev_b64 v[50:51], 12, v[50:51]
	v_lshlrev_b64 v[52:53], 12, v[52:53]
	v_lshl_add_u64 v[38:39], v[36:37], 0, v[38:39]
	v_lshl_add_u64 v[40:41], v[36:37], 0, v[40:41]
	v_lshl_add_u64 v[42:43], v[36:37], 0, v[42:43]
	v_lshl_add_u64 v[44:45], v[36:37], 0, v[44:45]
	v_lshl_add_u64 v[46:47], v[36:37], 0, v[46:47]
	v_lshl_add_u64 v[48:49], v[36:37], 0, v[48:49]
	v_lshl_add_u64 v[50:51], v[36:37], 0, v[50:51]
	v_lshl_add_u64 v[52:53], v[36:37], 0, v[52:53]
	global_load_dword v54, v[38:39], off nt
	global_load_dword v55, v[40:41], off nt
	global_load_dword v56, v[42:43], off nt
	global_load_dword v57, v[44:45], off nt
	global_load_dword v58, v[46:47], off nt
	global_load_dword v59, v[48:49], off nt
	global_load_dword v60, v[50:51], off nt
	global_load_dword v61, v[52:53], off nt
	v_or_b32_e32 v38, 16, v34
	v_mov_b32_e32 v39, v1
	v_or_b32_e32 v40, 18, v34
	v_mov_b32_e32 v41, v1
	v_or_b32_e32 v42, 20, v34
	v_mov_b32_e32 v43, v1
	v_or_b32_e32 v44, 22, v34
	v_mov_b32_e32 v45, v1
	v_or_b32_e32 v46, 24, v34
	v_mov_b32_e32 v47, v1
	v_or_b32_e32 v48, 26, v34
	v_mov_b32_e32 v49, v1
	v_or_b32_e32 v50, 28, v34
	v_mov_b32_e32 v51, v1
	v_or_b32_e32 v52, 30, v34
	v_mov_b32_e32 v53, v1
	v_lshlrev_b64 v[38:39], 12, v[38:39]
	v_lshlrev_b64 v[40:41], 12, v[40:41]
	v_lshlrev_b64 v[42:43], 12, v[42:43]
	v_lshlrev_b64 v[44:45], 12, v[44:45]
	v_lshlrev_b64 v[46:47], 12, v[46:47]
	v_lshlrev_b64 v[48:49], 12, v[48:49]
	v_lshlrev_b64 v[50:51], 12, v[50:51]
	v_lshlrev_b64 v[52:53], 12, v[52:53]
	v_lshl_add_u64 v[38:39], v[36:37], 0, v[38:39]
	v_lshl_add_u64 v[40:41], v[36:37], 0, v[40:41]
	v_lshl_add_u64 v[42:43], v[36:37], 0, v[42:43]
	v_lshl_add_u64 v[44:45], v[36:37], 0, v[44:45]
	v_lshl_add_u64 v[46:47], v[36:37], 0, v[46:47]
	v_lshl_add_u64 v[48:49], v[36:37], 0, v[48:49]
	v_lshl_add_u64 v[50:51], v[36:37], 0, v[50:51]
	v_lshl_add_u64 v[52:53], v[36:37], 0, v[52:53]
	global_load_dword v62, v[38:39], off nt
	global_load_dword v63, v[40:41], off nt
	global_load_dword v64, v[42:43], off nt
	global_load_dword v65, v[44:45], off nt
	global_load_dword v66, v[46:47], off nt
	global_load_dword v67, v[48:49], off nt
	global_load_dword v68, v[50:51], off nt
	global_load_dword v69, v[52:53], off nt
	v_or_b32_e32 v38, 32, v34
	v_mov_b32_e32 v39, v1
	v_or_b32_e32 v40, 34, v34
	v_mov_b32_e32 v41, v1
	v_or_b32_e32 v42, 36, v34
	v_mov_b32_e32 v43, v1
	v_or_b32_e32 v44, 38, v34
	v_mov_b32_e32 v45, v1
	v_or_b32_e32 v46, 40, v34
	v_mov_b32_e32 v47, v1
	v_or_b32_e32 v48, 42, v34
	v_mov_b32_e32 v49, v1
	v_or_b32_e32 v50, 44, v34
	v_mov_b32_e32 v51, v1
	v_or_b32_e32 v52, 46, v34
	v_mov_b32_e32 v53, v1
	v_lshlrev_b64 v[38:39], 12, v[38:39]
	v_lshlrev_b64 v[40:41], 12, v[40:41]
	v_lshlrev_b64 v[42:43], 12, v[42:43]
	v_lshlrev_b64 v[44:45], 12, v[44:45]
	v_lshlrev_b64 v[46:47], 12, v[46:47]
	v_lshlrev_b64 v[48:49], 12, v[48:49]
	v_lshlrev_b64 v[50:51], 12, v[50:51]
	v_lshlrev_b64 v[52:53], 12, v[52:53]
	v_lshl_add_u64 v[38:39], v[36:37], 0, v[38:39]
	v_lshl_add_u64 v[40:41], v[36:37], 0, v[40:41]
	v_lshl_add_u64 v[42:43], v[36:37], 0, v[42:43]
	v_lshl_add_u64 v[44:45], v[36:37], 0, v[44:45]
	v_lshl_add_u64 v[46:47], v[36:37], 0, v[46:47]
	v_lshl_add_u64 v[48:49], v[36:37], 0, v[48:49]
	v_lshl_add_u64 v[50:51], v[36:37], 0, v[50:51]
	v_lshl_add_u64 v[52:53], v[36:37], 0, v[52:53]
	global_load_dword v70, v[38:39], off nt
	global_load_dword v71, v[40:41], off nt
	global_load_dword v72, v[42:43], off nt
	global_load_dword v73, v[44:45], off nt
	global_load_dword v74, v[46:47], off nt
	global_load_dword v75, v[48:49], off nt
	global_load_dword v76, v[50:51], off nt
	s_nop 0
	global_load_dword v52, v[52:53], off nt
	v_or_b32_e32 v38, 48, v34
	v_mov_b32_e32 v39, v1
	v_or_b32_e32 v40, 50, v34
	v_mov_b32_e32 v41, v1
	v_or_b32_e32 v42, 52, v34
	v_mov_b32_e32 v43, v1
	v_or_b32_e32 v44, 54, v34
	v_or_b32_e32 v46, 56, v34
	v_or_b32_e32 v48, 58, v34
	v_or_b32_e32 v50, 60, v34
	v_or_b32_e32 v34, 62, v34
	v_lshlrev_b64 v[38:39], 12, v[38:39]
	v_lshlrev_b64 v[40:41], 12, v[40:41]
	v_lshlrev_b64 v[42:43], 12, v[42:43]
	v_mov_b32_e32 v45, v1
	v_mov_b32_e32 v47, v1
	v_mov_b32_e32 v49, v1
	v_mov_b32_e32 v51, v1
	v_lshlrev_b64 v[34:35], 12, v[34:35]
	v_lshl_add_u64 v[38:39], v[36:37], 0, v[38:39]
	v_lshl_add_u64 v[40:41], v[36:37], 0, v[40:41]
	v_lshl_add_u64 v[42:43], v[36:37], 0, v[42:43]
	v_lshlrev_b64 v[44:45], 12, v[44:45]
	v_lshlrev_b64 v[46:47], 12, v[46:47]
	v_lshlrev_b64 v[48:49], 12, v[48:49]
	v_lshlrev_b64 v[50:51], 12, v[50:51]
	v_lshl_add_u64 v[34:35], v[36:37], 0, v[34:35]
	v_lshl_add_u64 v[44:45], v[36:37], 0, v[44:45]
	v_lshl_add_u64 v[46:47], v[36:37], 0, v[46:47]
	v_lshl_add_u64 v[48:49], v[36:37], 0, v[48:49]
	v_lshl_add_u64 v[50:51], v[36:37], 0, v[50:51]
	global_load_dword v36, v[38:39], off nt
	global_load_dword v37, v[40:41], off nt
	s_nop 0
	global_load_dword v38, v[42:43], off nt
	global_load_dword v39, v[44:45], off nt
	global_load_dword v40, v[46:47], off nt
	global_load_dword v41, v[48:49], off nt
	s_nop 0
	global_load_dword v42, v[50:51], off nt
	s_nop 0
	global_load_dword v34, v[34:35], off nt
	s_waitcnt vmcnt(30)
	ds_write2_b32 v130, v54, v55 offset1:66
	s_waitcnt vmcnt(28)
	ds_write2_b32 v130, v56, v57 offset0:132 offset1:198
	s_waitcnt vmcnt(26)
	ds_write2_b32 v136, v58, v59 offset0:8 offset1:74
	s_waitcnt vmcnt(24)
	ds_write2_b32 v136, v60, v61 offset0:140 offset1:206
	s_waitcnt vmcnt(22)
	ds_write2_b32 v137, v62, v63 offset0:16 offset1:82
	s_waitcnt vmcnt(20)
	ds_write2_b32 v137, v64, v65 offset0:148 offset1:214
	s_waitcnt vmcnt(18)
	ds_write2_b32 v138, v66, v67 offset0:24 offset1:90
	s_waitcnt vmcnt(16)
	ds_write2_b32 v138, v68, v69 offset0:156 offset1:222
	s_waitcnt vmcnt(14)
	ds_write2_b32 v139, v70, v71 offset0:32 offset1:98
	s_waitcnt vmcnt(12)
	ds_write2_b32 v139, v72, v73 offset0:164 offset1:230
	s_waitcnt vmcnt(10)
	ds_write2_b32 v140, v74, v75 offset0:40 offset1:106
	s_waitcnt vmcnt(8)
	ds_write2_b32 v140, v76, v52 offset0:172 offset1:238
	s_waitcnt vmcnt(6)
	ds_write2_b32 v141, v36, v37 offset0:48 offset1:114
	s_waitcnt vmcnt(4)
	ds_write2_b32 v141, v38, v39 offset0:180 offset1:246
	s_waitcnt vmcnt(2)
	ds_write2_b32 v142, v40, v41 offset0:56 offset1:122
	s_waitcnt vmcnt(0)
	ds_write2_b32 v142, v42, v34 offset0:188 offset1:254
	s_waitcnt lgkmcnt(0)
	ds_read2_b32 v[38:39], v132 offset0:33 offset1:41
	ds_read2_b32 v[40:41], v132 offset1:8
	ds_read2_b32 v[42:43], v132 offset0:66 offset1:74
	ds_read2_b32 v[44:45], v132 offset0:99 offset1:107
	ds_read2_b32 v[46:47], v132 offset0:132 offset1:140
	ds_read2_b32 v[48:49], v132 offset0:165 offset1:173
	ds_read2_b32 v[50:51], v132 offset0:198 offset1:206
	ds_read2_b32 v[52:53], v132 offset0:231 offset1:239
	s_mov_b32 s11, s1
	s_waitcnt lgkmcnt(6)
	v_cvt_pk_bf16_f32 v34, v40, v38
	v_or_b32_e32 v38, s22, v131
	v_lshl_add_u64 v[54:55], s[10:11], 1, v[20:21]
	v_lshlrev_b32_e32 v56, 11, v38
	v_mov_b32_e32 v57, v1
	s_waitcnt lgkmcnt(4)
	v_cvt_pk_bf16_f32 v35, v42, v44
	s_waitcnt lgkmcnt(2)
	v_cvt_pk_bf16_f32 v36, v46, v48
	s_waitcnt lgkmcnt(0)
	v_cvt_pk_bf16_f32 v37, v50, v52
	v_lshl_add_u64 v[56:57], v[54:55], 0, v[56:57]
	global_store_dwordx4 v[56:57], v[34:37], off sc0 sc1
	v_or_b32_e32 v38, s22, v133
	v_lshlrev_b32_e32 v38, 11, v38
	v_cvt_pk_bf16_f32 v34, v41, v39
	v_cvt_pk_bf16_f32 v35, v43, v45
	v_cvt_pk_bf16_f32 v36, v47, v49
	v_cvt_pk_bf16_f32 v37, v51, v53
	ds_read2_b32 v[40:41], v132 offset0:49 offset1:57
	ds_read2_b32 v[42:43], v132 offset0:16 offset1:24
	ds_read2_b32 v[44:45], v132 offset0:82 offset1:90
	ds_read2_b32 v[46:47], v132 offset0:115 offset1:123
	ds_read2_b32 v[48:49], v132 offset0:148 offset1:156
	ds_read2_b32 v[50:51], v132 offset0:181 offset1:189
	ds_read2_b32 v[52:53], v132 offset0:214 offset1:222
	ds_read2_b32 v[56:57], v132 offset0:247 offset1:255
	v_mov_b32_e32 v39, v1
	v_lshl_add_u64 v[38:39], v[54:55], 0, v[38:39]
	global_store_dwordx4 v[38:39], v[34:37], off sc0 sc1
	v_or_b32_e32 v38, s22, v134
	v_lshlrev_b32_e32 v38, 11, v38
	v_mov_b32_e32 v39, v1
	s_waitcnt lgkmcnt(6)
	v_cvt_pk_bf16_f32 v34, v42, v40
	s_waitcnt lgkmcnt(4)
	v_cvt_pk_bf16_f32 v35, v44, v46
	s_waitcnt lgkmcnt(2)
	v_cvt_pk_bf16_f32 v36, v48, v50
	s_waitcnt lgkmcnt(0)
	v_cvt_pk_bf16_f32 v37, v52, v56
	v_lshl_add_u64 v[38:39], v[54:55], 0, v[38:39]
	global_store_dwordx4 v[38:39], v[34:37], off sc0 sc1
	v_or_b32_e32 v38, s22, v135
	v_lshlrev_b32_e32 v38, 11, v38
	v_mov_b32_e32 v39, v1
	v_cvt_pk_bf16_f32 v34, v43, v41
	v_cvt_pk_bf16_f32 v35, v45, v47
	v_cvt_pk_bf16_f32 v36, v49, v51
	v_cvt_pk_bf16_f32 v37, v53, v57
	v_lshl_add_u64 v[38:39], v[54:55], 0, v[38:39]
	global_store_dwordx4 v[38:39], v[34:37], off sc0 sc1
	s_waitcnt lgkmcnt(0)

.LBB0_44:
	s_andn2_b64 vcc, exec, s[10:11]
	s_cbranch_vccnz .LBB0_46
	s_and_b32 s0, s16, 0x1fc0
	s_add_i32 s10, s0, 0xffffe800
	s_and_b32 s22, s12, 0x3e0
	v_or_b32_e32 v34, s10, v17
	s_lshl_b32 s0, s22, 2
	v_mov_b32_e32 v35, v1
	v_or_b32_e32 v40, 2, v34
	v_mov_b32_e32 v41, v1
	v_or_b32_e32 v42, 4, v34
	v_mov_b32_e32 v43, v1
	v_or_b32_e32 v44, 6, v34
	v_mov_b32_e32 v45, v1
	v_or_b32_e32 v46, 8, v34
	v_mov_b32_e32 v47, v1
	v_or_b32_e32 v48, 10, v34
	v_mov_b32_e32 v49, v1
	v_or_b32_e32 v50, 12, v34
	v_mov_b32_e32 v51, v1
	v_or_b32_e32 v52, 14, v34
	v_mov_b32_e32 v53, v1
	v_lshl_add_u64 v[36:37], v[22:23], 0, s[0:1]
	v_lshlrev_b64 v[38:39], 12, v[34:35]
	v_lshlrev_b64 v[40:41], 12, v[40:41]
	v_lshlrev_b64 v[42:43], 12, v[42:43]
	v_lshlrev_b64 v[44:45], 12, v[44:45]
	v_lshlrev_b64 v[46:47], 12, v[46:47]
	v_lshlrev_b64 v[48:49], 12, v[48:49]
	v_lshlrev_b64 v[50:51], 12, v[50:51]
	v_lshlrev_b64 v[52:53], 12, v[52:53]
	v_lshl_add_u64 v[38:39], v[36:37], 0, v[38:39]
	v_lshl_add_u64 v[40:41], v[36:37], 0, v[40:41]
	v_lshl_add_u64 v[42:43], v[36:37], 0, v[42:43]
	v_lshl_add_u64 v[44:45], v[36:37], 0, v[44:45]
	v_lshl_add_u64 v[46:47], v[36:37], 0, v[46:47]
	v_lshl_add_u64 v[48:49], v[36:37], 0, v[48:49]
	v_lshl_add_u64 v[50:51], v[36:37], 0, v[50:51]
	v_lshl_add_u64 v[52:53], v[36:37], 0, v[52:53]
	global_load_dword v54, v[38:39], off nt
	global_load_dword v55, v[40:41], off nt
	global_load_dword v56, v[42:43], off nt
	global_load_dword v57, v[44:45], off nt
	global_load_dword v58, v[46:47], off nt
	global_load_dword v59, v[48:49], off nt
	global_load_dword v60, v[50:51], off nt
	global_load_dword v61, v[52:53], off nt
	v_or_b32_e32 v38, 16, v34
	v_mov_b32_e32 v39, v1
	v_or_b32_e32 v40, 18, v34
	v_mov_b32_e32 v41, v1
	v_or_b32_e32 v42, 20, v34
	v_mov_b32_e32 v43, v1
	v_or_b32_e32 v44, 22, v34
	v_mov_b32_e32 v45, v1
	v_or_b32_e32 v46, 24, v34
	v_mov_b32_e32 v47, v1
	v_or_b32_e32 v48, 26, v34
	v_mov_b32_e32 v49, v1
	v_or_b32_e32 v50, 28, v34
	v_mov_b32_e32 v51, v1
	v_or_b32_e32 v52, 30, v34
	v_mov_b32_e32 v53, v1
	v_lshlrev_b64 v[38:39], 12, v[38:39]
	v_lshlrev_b64 v[40:41], 12, v[40:41]
	v_lshlrev_b64 v[42:43], 12, v[42:43]
	v_lshlrev_b64 v[44:45], 12, v[44:45]
	v_lshlrev_b64 v[46:47], 12, v[46:47]
	v_lshlrev_b64 v[48:49], 12, v[48:49]
	v_lshlrev_b64 v[50:51], 12, v[50:51]
	v_lshlrev_b64 v[52:53], 12, v[52:53]
	v_lshl_add_u64 v[38:39], v[36:37], 0, v[38:39]
	v_lshl_add_u64 v[40:41], v[36:37], 0, v[40:41]
	v_lshl_add_u64 v[42:43], v[36:37], 0, v[42:43]
	v_lshl_add_u64 v[44:45], v[36:37], 0, v[44:45]
	v_lshl_add_u64 v[46:47], v[36:37], 0, v[46:47]
	v_lshl_add_u64 v[48:49], v[36:37], 0, v[48:49]
	v_lshl_add_u64 v[50:51], v[36:37], 0, v[50:51]
	v_lshl_add_u64 v[52:53], v[36:37], 0, v[52:53]
	global_load_dword v62, v[38:39], off nt
	global_load_dword v63, v[40:41], off nt
	global_load_dword v64, v[42:43], off nt
	global_load_dword v65, v[44:45], off nt
	global_load_dword v66, v[46:47], off nt
	global_load_dword v67, v[48:49], off nt
	global_load_dword v68, v[50:51], off nt
	global_load_dword v69, v[52:53], off nt
	v_or_b32_e32 v38, 32, v34
	v_mov_b32_e32 v39, v1
	v_or_b32_e32 v40, 34, v34
	v_mov_b32_e32 v41, v1
	v_or_b32_e32 v42, 36, v34
	v_mov_b32_e32 v43, v1
	v_or_b32_e32 v44, 38, v34
	v_mov_b32_e32 v45, v1
	v_or_b32_e32 v46, 40, v34
	v_mov_b32_e32 v47, v1
	v_or_b32_e32 v48, 42, v34
	v_mov_b32_e32 v49, v1
	v_or_b32_e32 v50, 44, v34
	v_mov_b32_e32 v51, v1
	v_or_b32_e32 v52, 46, v34
	v_mov_b32_e32 v53, v1
	v_lshlrev_b64 v[38:39], 12, v[38:39]
	v_lshlrev_b64 v[40:41], 12, v[40:41]
	v_lshlrev_b64 v[42:43], 12, v[42:43]
	v_lshlrev_b64 v[44:45], 12, v[44:45]
	v_lshlrev_b64 v[46:47], 12, v[46:47]
	v_lshlrev_b64 v[48:49], 12, v[48:49]
	v_lshlrev_b64 v[50:51], 12, v[50:51]
	v_lshlrev_b64 v[52:53], 12, v[52:53]
	v_lshl_add_u64 v[38:39], v[36:37], 0, v[38:39]
	v_lshl_add_u64 v[40:41], v[36:37], 0, v[40:41]
	v_lshl_add_u64 v[42:43], v[36:37], 0, v[42:43]
	v_lshl_add_u64 v[44:45], v[36:37], 0, v[44:45]
	v_lshl_add_u64 v[46:47], v[36:37], 0, v[46:47]
	v_lshl_add_u64 v[48:49], v[36:37], 0, v[48:49]
	v_lshl_add_u64 v[50:51], v[36:37], 0, v[50:51]
	v_lshl_add_u64 v[52:53], v[36:37], 0, v[52:53]
	global_load_dword v70, v[38:39], off nt
	global_load_dword v71, v[40:41], off nt
	global_load_dword v72, v[42:43], off nt
	global_load_dword v73, v[44:45], off nt
	global_load_dword v74, v[46:47], off nt
	global_load_dword v75, v[48:49], off nt
	global_load_dword v76, v[50:51], off nt
	s_nop 0
	global_load_dword v52, v[52:53], off nt
	v_or_b32_e32 v38, 48, v34
	v_mov_b32_e32 v39, v1
	v_or_b32_e32 v40, 50, v34
	v_mov_b32_e32 v41, v1
	v_or_b32_e32 v42, 52, v34
	v_mov_b32_e32 v43, v1
	v_or_b32_e32 v44, 54, v34
	v_or_b32_e32 v46, 56, v34
	v_or_b32_e32 v48, 58, v34
	v_or_b32_e32 v50, 60, v34
	v_or_b32_e32 v34, 62, v34
	v_lshlrev_b64 v[38:39], 12, v[38:39]
	v_lshlrev_b64 v[40:41], 12, v[40:41]
	v_lshlrev_b64 v[42:43], 12, v[42:43]
	v_mov_b32_e32 v45, v1
	v_mov_b32_e32 v47, v1
	v_mov_b32_e32 v49, v1
	v_mov_b32_e32 v51, v1
	v_lshlrev_b64 v[34:35], 12, v[34:35]
	v_lshl_add_u64 v[38:39], v[36:37], 0, v[38:39]
	v_lshl_add_u64 v[40:41], v[36:37], 0, v[40:41]
	v_lshl_add_u64 v[42:43], v[36:37], 0, v[42:43]
	v_lshlrev_b64 v[44:45], 12, v[44:45]
	v_lshlrev_b64 v[46:47], 12, v[46:47]
	v_lshlrev_b64 v[48:49], 12, v[48:49]
	v_lshlrev_b64 v[50:51], 12, v[50:51]
	v_lshl_add_u64 v[34:35], v[36:37], 0, v[34:35]
	v_lshl_add_u64 v[44:45], v[36:37], 0, v[44:45]
	v_lshl_add_u64 v[46:47], v[36:37], 0, v[46:47]
	v_lshl_add_u64 v[48:49], v[36:37], 0, v[48:49]
	v_lshl_add_u64 v[50:51], v[36:37], 0, v[50:51]
	global_load_dword v36, v[38:39], off nt
	global_load_dword v37, v[40:41], off nt
	s_nop 0
	global_load_dword v38, v[42:43], off nt
	global_load_dword v39, v[44:45], off nt
	global_load_dword v40, v[46:47], off nt
	global_load_dword v41, v[48:49], off nt
	s_nop 0
	global_load_dword v42, v[50:51], off nt
	s_nop 0
	global_load_dword v34, v[34:35], off nt
	s_waitcnt vmcnt(30)
	ds_write2_b32 v130, v54, v55 offset1:66
	s_waitcnt vmcnt(28)
	ds_write2_b32 v130, v56, v57 offset0:132 offset1:198
	s_waitcnt vmcnt(26)
	ds_write2_b32 v136, v58, v59 offset0:8 offset1:74
	s_waitcnt vmcnt(24)
	ds_write2_b32 v136, v60, v61 offset0:140 offset1:206
	s_waitcnt vmcnt(22)
	ds_write2_b32 v137, v62, v63 offset0:16 offset1:82
	s_waitcnt vmcnt(20)
	ds_write2_b32 v137, v64, v65 offset0:148 offset1:214
	s_waitcnt vmcnt(18)
	ds_write2_b32 v138, v66, v67 offset0:24 offset1:90
	s_waitcnt vmcnt(16)
	ds_write2_b32 v138, v68, v69 offset0:156 offset1:222
	s_waitcnt vmcnt(14)
	ds_write2_b32 v139, v70, v71 offset0:32 offset1:98
	s_waitcnt vmcnt(12)
	ds_write2_b32 v139, v72, v73 offset0:164 offset1:230
	s_waitcnt vmcnt(10)
	ds_write2_b32 v140, v74, v75 offset0:40 offset1:106
	s_waitcnt vmcnt(8)
	ds_write2_b32 v140, v76, v52 offset0:172 offset1:238
	s_waitcnt vmcnt(6)
	ds_write2_b32 v141, v36, v37 offset0:48 offset1:114
	s_waitcnt vmcnt(4)
	ds_write2_b32 v141, v38, v39 offset0:180 offset1:246
	s_waitcnt vmcnt(2)
	ds_write2_b32 v142, v40, v41 offset0:56 offset1:122
	s_waitcnt vmcnt(0)
	ds_write2_b32 v142, v42, v34 offset0:188 offset1:254
	s_waitcnt lgkmcnt(0)
	ds_read2_b32 v[38:39], v132 offset0:33 offset1:41
	ds_read2_b32 v[40:41], v132 offset1:8
	ds_read2_b32 v[42:43], v132 offset0:66 offset1:74
	ds_read2_b32 v[44:45], v132 offset0:99 offset1:107
	ds_read2_b32 v[46:47], v132 offset0:132 offset1:140
	ds_read2_b32 v[48:49], v132 offset0:165 offset1:173
	ds_read2_b32 v[50:51], v132 offset0:198 offset1:206
	ds_read2_b32 v[52:53], v132 offset0:231 offset1:239
	s_mov_b32 s11, s1
	s_waitcnt lgkmcnt(6)
	v_cvt_pk_bf16_f32 v34, v40, v38
	v_or_b32_e32 v38, s22, v131
	v_lshl_add_u64 v[54:55], s[10:11], 1, v[24:25]
	v_lshlrev_b32_e32 v56, 10, v38
	v_mov_b32_e32 v57, v1
	s_waitcnt lgkmcnt(4)
	v_cvt_pk_bf16_f32 v35, v42, v44
	s_waitcnt lgkmcnt(2)
	v_cvt_pk_bf16_f32 v36, v46, v48
	s_waitcnt lgkmcnt(0)
	v_cvt_pk_bf16_f32 v37, v50, v52
	v_lshl_add_u64 v[56:57], v[54:55], 0, v[56:57]
	global_store_dwordx4 v[56:57], v[34:37], off sc0 sc1
	v_or_b32_e32 v38, s22, v133
	v_lshlrev_b32_e32 v38, 10, v38
	v_cvt_pk_bf16_f32 v34, v41, v39
	v_cvt_pk_bf16_f32 v35, v43, v45
	v_cvt_pk_bf16_f32 v36, v47, v49
	v_cvt_pk_bf16_f32 v37, v51, v53
	ds_read2_b32 v[40:41], v132 offset0:49 offset1:57
	ds_read2_b32 v[42:43], v132 offset0:16 offset1:24
	ds_read2_b32 v[44:45], v132 offset0:82 offset1:90
	ds_read2_b32 v[46:47], v132 offset0:115 offset1:123
	ds_read2_b32 v[48:49], v132 offset0:148 offset1:156
	ds_read2_b32 v[50:51], v132 offset0:181 offset1:189
	ds_read2_b32 v[52:53], v132 offset0:214 offset1:222
	ds_read2_b32 v[56:57], v132 offset0:247 offset1:255
	v_mov_b32_e32 v39, v1
	v_lshl_add_u64 v[38:39], v[54:55], 0, v[38:39]
	global_store_dwordx4 v[38:39], v[34:37], off sc0 sc1
	v_or_b32_e32 v38, s22, v134
	v_lshlrev_b32_e32 v38, 10, v38
	v_mov_b32_e32 v39, v1
	s_waitcnt lgkmcnt(6)
	v_cvt_pk_bf16_f32 v34, v42, v40
	s_waitcnt lgkmcnt(4)
	v_cvt_pk_bf16_f32 v35, v44, v46
	s_waitcnt lgkmcnt(2)
	v_cvt_pk_bf16_f32 v36, v48, v50
	s_waitcnt lgkmcnt(0)
	v_cvt_pk_bf16_f32 v37, v52, v56
	v_lshl_add_u64 v[38:39], v[54:55], 0, v[38:39]
	global_store_dwordx4 v[38:39], v[34:37], off sc0 sc1
	v_or_b32_e32 v38, s22, v135
	v_lshlrev_b32_e32 v38, 10, v38
	v_mov_b32_e32 v39, v1
	v_cvt_pk_bf16_f32 v34, v43, v41
	v_cvt_pk_bf16_f32 v35, v45, v47
	v_cvt_pk_bf16_f32 v36, v49, v51
	v_cvt_pk_bf16_f32 v37, v53, v57
	v_lshl_add_u64 v[38:39], v[54:55], 0, v[38:39]
	global_store_dwordx4 v[38:39], v[34:37], off sc0 sc1
	s_waitcnt lgkmcnt(0)

.LBB0_47:
	s_andn2_b64 vcc, exec, s[10:11]
	s_cbranch_vccnz .LBB0_49
	s_and_b32 s0, s16, 0x1fc0
	s_add_i32 s10, s0, 0xffffea00
	s_and_b32 s22, s12, 0x3e0
	v_or_b32_e32 v34, s10, v17
	s_lshl_b32 s0, s22, 2
	v_mov_b32_e32 v35, v1
	v_or_b32_e32 v40, 2, v34
	v_mov_b32_e32 v41, v1
	v_or_b32_e32 v42, 4, v34
	v_mov_b32_e32 v43, v1
	v_or_b32_e32 v44, 6, v34
	v_mov_b32_e32 v45, v1
	v_or_b32_e32 v46, 8, v34
	v_mov_b32_e32 v47, v1
	v_or_b32_e32 v48, 10, v34
	v_mov_b32_e32 v49, v1
	v_or_b32_e32 v50, 12, v34
	v_mov_b32_e32 v51, v1
	v_or_b32_e32 v52, 14, v34
	v_mov_b32_e32 v53, v1
	v_lshl_add_u64 v[36:37], v[26:27], 0, s[0:1]
	v_lshlrev_b64 v[38:39], 12, v[34:35]
	v_lshlrev_b64 v[40:41], 12, v[40:41]
	v_lshlrev_b64 v[42:43], 12, v[42:43]
	v_lshlrev_b64 v[44:45], 12, v[44:45]
	v_lshlrev_b64 v[46:47], 12, v[46:47]
	v_lshlrev_b64 v[48:49], 12, v[48:49]
	v_lshlrev_b64 v[50:51], 12, v[50:51]
	v_lshlrev_b64 v[52:53], 12, v[52:53]
	v_lshl_add_u64 v[38:39], v[36:37], 0, v[38:39]
	v_lshl_add_u64 v[40:41], v[36:37], 0, v[40:41]
	v_lshl_add_u64 v[42:43], v[36:37], 0, v[42:43]
	v_lshl_add_u64 v[44:45], v[36:37], 0, v[44:45]
	v_lshl_add_u64 v[46:47], v[36:37], 0, v[46:47]
	v_lshl_add_u64 v[48:49], v[36:37], 0, v[48:49]
	v_lshl_add_u64 v[50:51], v[36:37], 0, v[50:51]
	v_lshl_add_u64 v[52:53], v[36:37], 0, v[52:53]
	global_load_dword v54, v[38:39], off nt
	global_load_dword v55, v[40:41], off nt
	global_load_dword v56, v[42:43], off nt
	global_load_dword v57, v[44:45], off nt
	global_load_dword v58, v[46:47], off nt
	global_load_dword v59, v[48:49], off nt
	global_load_dword v60, v[50:51], off nt
	global_load_dword v61, v[52:53], off nt
	v_or_b32_e32 v38, 16, v34
	v_mov_b32_e32 v39, v1
	v_or_b32_e32 v40, 18, v34
	v_mov_b32_e32 v41, v1
	v_or_b32_e32 v42, 20, v34
	v_mov_b32_e32 v43, v1
	v_or_b32_e32 v44, 22, v34
	v_mov_b32_e32 v45, v1
	v_or_b32_e32 v46, 24, v34
	v_mov_b32_e32 v47, v1
	v_or_b32_e32 v48, 26, v34
	v_mov_b32_e32 v49, v1
	v_or_b32_e32 v50, 28, v34
	v_mov_b32_e32 v51, v1
	v_or_b32_e32 v52, 30, v34
	v_mov_b32_e32 v53, v1
	v_lshlrev_b64 v[38:39], 12, v[38:39]
	v_lshlrev_b64 v[40:41], 12, v[40:41]
	v_lshlrev_b64 v[42:43], 12, v[42:43]
	v_lshlrev_b64 v[44:45], 12, v[44:45]
	v_lshlrev_b64 v[46:47], 12, v[46:47]
	v_lshlrev_b64 v[48:49], 12, v[48:49]
	v_lshlrev_b64 v[50:51], 12, v[50:51]
	v_lshlrev_b64 v[52:53], 12, v[52:53]
	v_lshl_add_u64 v[38:39], v[36:37], 0, v[38:39]
	v_lshl_add_u64 v[40:41], v[36:37], 0, v[40:41]
	v_lshl_add_u64 v[42:43], v[36:37], 0, v[42:43]
	v_lshl_add_u64 v[44:45], v[36:37], 0, v[44:45]
	v_lshl_add_u64 v[46:47], v[36:37], 0, v[46:47]
	v_lshl_add_u64 v[48:49], v[36:37], 0, v[48:49]
	v_lshl_add_u64 v[50:51], v[36:37], 0, v[50:51]
	v_lshl_add_u64 v[52:53], v[36:37], 0, v[52:53]
	global_load_dword v62, v[38:39], off nt
	global_load_dword v63, v[40:41], off nt
	global_load_dword v64, v[42:43], off nt
	global_load_dword v65, v[44:45], off nt
	global_load_dword v66, v[46:47], off nt
	global_load_dword v67, v[48:49], off nt
	global_load_dword v68, v[50:51], off nt
	global_load_dword v69, v[52:53], off nt
	v_or_b32_e32 v38, 32, v34
	v_mov_b32_e32 v39, v1
	v_or_b32_e32 v40, 34, v34
	v_mov_b32_e32 v41, v1
	v_or_b32_e32 v42, 36, v34
	v_mov_b32_e32 v43, v1
	v_or_b32_e32 v44, 38, v34
	v_mov_b32_e32 v45, v1
	v_or_b32_e32 v46, 40, v34
	v_mov_b32_e32 v47, v1
	v_or_b32_e32 v48, 42, v34
	v_mov_b32_e32 v49, v1
	v_or_b32_e32 v50, 44, v34
	v_mov_b32_e32 v51, v1
	v_or_b32_e32 v52, 46, v34
	v_mov_b32_e32 v53, v1
	v_lshlrev_b64 v[38:39], 12, v[38:39]
	v_lshlrev_b64 v[40:41], 12, v[40:41]
	v_lshlrev_b64 v[42:43], 12, v[42:43]
	v_lshlrev_b64 v[44:45], 12, v[44:45]
	v_lshlrev_b64 v[46:47], 12, v[46:47]
	v_lshlrev_b64 v[48:49], 12, v[48:49]
	v_lshlrev_b64 v[50:51], 12, v[50:51]
	v_lshlrev_b64 v[52:53], 12, v[52:53]
	v_lshl_add_u64 v[38:39], v[36:37], 0, v[38:39]
	v_lshl_add_u64 v[40:41], v[36:37], 0, v[40:41]
	v_lshl_add_u64 v[42:43], v[36:37], 0, v[42:43]
	v_lshl_add_u64 v[44:45], v[36:37], 0, v[44:45]
	v_lshl_add_u64 v[46:47], v[36:37], 0, v[46:47]
	v_lshl_add_u64 v[48:49], v[36:37], 0, v[48:49]
	v_lshl_add_u64 v[50:51], v[36:37], 0, v[50:51]
	v_lshl_add_u64 v[52:53], v[36:37], 0, v[52:53]
	global_load_dword v70, v[38:39], off nt
	global_load_dword v71, v[40:41], off nt
	global_load_dword v72, v[42:43], off nt
	global_load_dword v73, v[44:45], off nt
	global_load_dword v74, v[46:47], off nt
	global_load_dword v75, v[48:49], off nt
	global_load_dword v76, v[50:51], off nt
	s_nop 0
	global_load_dword v52, v[52:53], off nt
	v_or_b32_e32 v38, 48, v34
	v_mov_b32_e32 v39, v1
	v_or_b32_e32 v40, 50, v34
	v_mov_b32_e32 v41, v1
	v_or_b32_e32 v42, 52, v34
	v_mov_b32_e32 v43, v1
	v_or_b32_e32 v44, 54, v34
	v_or_b32_e32 v46, 56, v34
	v_or_b32_e32 v48, 58, v34
	v_or_b32_e32 v50, 60, v34
	v_or_b32_e32 v34, 62, v34
	v_lshlrev_b64 v[38:39], 12, v[38:39]
	v_lshlrev_b64 v[40:41], 12, v[40:41]
	v_lshlrev_b64 v[42:43], 12, v[42:43]
	v_mov_b32_e32 v45, v1
	v_mov_b32_e32 v47, v1
	v_mov_b32_e32 v49, v1
	v_mov_b32_e32 v51, v1
	v_lshlrev_b64 v[34:35], 12, v[34:35]
	v_lshl_add_u64 v[38:39], v[36:37], 0, v[38:39]
	v_lshl_add_u64 v[40:41], v[36:37], 0, v[40:41]
	v_lshl_add_u64 v[42:43], v[36:37], 0, v[42:43]
	v_lshlrev_b64 v[44:45], 12, v[44:45]
	v_lshlrev_b64 v[46:47], 12, v[46:47]
	v_lshlrev_b64 v[48:49], 12, v[48:49]
	v_lshlrev_b64 v[50:51], 12, v[50:51]
	v_lshl_add_u64 v[34:35], v[36:37], 0, v[34:35]
	v_lshl_add_u64 v[44:45], v[36:37], 0, v[44:45]
	v_lshl_add_u64 v[46:47], v[36:37], 0, v[46:47]
	v_lshl_add_u64 v[48:49], v[36:37], 0, v[48:49]
	v_lshl_add_u64 v[50:51], v[36:37], 0, v[50:51]
	global_load_dword v36, v[38:39], off nt
	global_load_dword v37, v[40:41], off nt
	s_nop 0
	global_load_dword v38, v[42:43], off nt
	global_load_dword v39, v[44:45], off nt
	global_load_dword v40, v[46:47], off nt
	global_load_dword v41, v[48:49], off nt
	s_nop 0
	global_load_dword v42, v[50:51], off nt
	s_nop 0
	global_load_dword v34, v[34:35], off nt
	s_waitcnt vmcnt(30)
	ds_write2_b32 v130, v54, v55 offset1:66
	s_waitcnt vmcnt(28)
	ds_write2_b32 v130, v56, v57 offset0:132 offset1:198
	s_waitcnt vmcnt(26)
	ds_write2_b32 v136, v58, v59 offset0:8 offset1:74
	s_waitcnt vmcnt(24)
	ds_write2_b32 v136, v60, v61 offset0:140 offset1:206
	s_waitcnt vmcnt(22)
	ds_write2_b32 v137, v62, v63 offset0:16 offset1:82
	s_waitcnt vmcnt(20)
	ds_write2_b32 v137, v64, v65 offset0:148 offset1:214
	s_waitcnt vmcnt(18)
	ds_write2_b32 v138, v66, v67 offset0:24 offset1:90
	s_waitcnt vmcnt(16)
	ds_write2_b32 v138, v68, v69 offset0:156 offset1:222
	s_waitcnt vmcnt(14)
	ds_write2_b32 v139, v70, v71 offset0:32 offset1:98
	s_waitcnt vmcnt(12)
	ds_write2_b32 v139, v72, v73 offset0:164 offset1:230
	s_waitcnt vmcnt(10)
	ds_write2_b32 v140, v74, v75 offset0:40 offset1:106
	s_waitcnt vmcnt(8)
	ds_write2_b32 v140, v76, v52 offset0:172 offset1:238
	s_waitcnt vmcnt(6)
	ds_write2_b32 v141, v36, v37 offset0:48 offset1:114
	s_waitcnt vmcnt(4)
	ds_write2_b32 v141, v38, v39 offset0:180 offset1:246
	s_waitcnt vmcnt(2)
	ds_write2_b32 v142, v40, v41 offset0:56 offset1:122
	s_waitcnt vmcnt(0)
	ds_write2_b32 v142, v42, v34 offset0:188 offset1:254
	s_waitcnt lgkmcnt(0)
	ds_read2_b32 v[38:39], v132 offset0:33 offset1:41
	ds_read2_b32 v[40:41], v132 offset1:8
	ds_read2_b32 v[42:43], v132 offset0:66 offset1:74
	ds_read2_b32 v[44:45], v132 offset0:99 offset1:107
	ds_read2_b32 v[46:47], v132 offset0:132 offset1:140
	ds_read2_b32 v[48:49], v132 offset0:165 offset1:173
	ds_read2_b32 v[50:51], v132 offset0:198 offset1:206
	ds_read2_b32 v[52:53], v132 offset0:231 offset1:239
	s_mov_b32 s11, s1
	s_waitcnt lgkmcnt(6)
	v_cvt_pk_bf16_f32 v34, v40, v38
	v_or_b32_e32 v38, s22, v131
	v_lshl_add_u64 v[54:55], s[10:11], 1, v[28:29]
	v_lshlrev_b32_e32 v56, 10, v38
	v_mov_b32_e32 v57, v1
	s_waitcnt lgkmcnt(4)
	v_cvt_pk_bf16_f32 v35, v42, v44
	s_waitcnt lgkmcnt(2)
	v_cvt_pk_bf16_f32 v36, v46, v48
	s_waitcnt lgkmcnt(0)
	v_cvt_pk_bf16_f32 v37, v50, v52
	v_lshl_add_u64 v[56:57], v[54:55], 0, v[56:57]
	global_store_dwordx4 v[56:57], v[34:37], off sc0 sc1
	v_or_b32_e32 v38, s22, v133
	v_lshlrev_b32_e32 v38, 10, v38
	v_cvt_pk_bf16_f32 v34, v41, v39
	v_cvt_pk_bf16_f32 v35, v43, v45
	v_cvt_pk_bf16_f32 v36, v47, v49
	v_cvt_pk_bf16_f32 v37, v51, v53
	ds_read2_b32 v[40:41], v132 offset0:49 offset1:57
	ds_read2_b32 v[42:43], v132 offset0:16 offset1:24
	ds_read2_b32 v[44:45], v132 offset0:82 offset1:90
	ds_read2_b32 v[46:47], v132 offset0:115 offset1:123
	ds_read2_b32 v[48:49], v132 offset0:148 offset1:156
	ds_read2_b32 v[50:51], v132 offset0:181 offset1:189
	ds_read2_b32 v[52:53], v132 offset0:214 offset1:222
	ds_read2_b32 v[56:57], v132 offset0:247 offset1:255
	v_mov_b32_e32 v39, v1
	v_lshl_add_u64 v[38:39], v[54:55], 0, v[38:39]
	global_store_dwordx4 v[38:39], v[34:37], off sc0 sc1
	v_or_b32_e32 v38, s22, v134
	v_lshlrev_b32_e32 v38, 10, v38
	v_mov_b32_e32 v39, v1
	s_waitcnt lgkmcnt(6)
	v_cvt_pk_bf16_f32 v34, v42, v40
	s_waitcnt lgkmcnt(4)
	v_cvt_pk_bf16_f32 v35, v44, v46
	s_waitcnt lgkmcnt(2)
	v_cvt_pk_bf16_f32 v36, v48, v50
	s_waitcnt lgkmcnt(0)
	v_cvt_pk_bf16_f32 v37, v52, v56
	v_lshl_add_u64 v[38:39], v[54:55], 0, v[38:39]
	global_store_dwordx4 v[38:39], v[34:37], off sc0 sc1
	v_or_b32_e32 v38, s22, v135
	v_lshlrev_b32_e32 v38, 10, v38
	v_mov_b32_e32 v39, v1
	v_cvt_pk_bf16_f32 v34, v43, v41
	v_cvt_pk_bf16_f32 v35, v45, v47
	v_cvt_pk_bf16_f32 v36, v49, v51
	v_cvt_pk_bf16_f32 v37, v53, v57
	v_lshl_add_u64 v[38:39], v[54:55], 0, v[38:39]
	global_store_dwordx4 v[38:39], v[34:37], off sc0 sc1
	s_waitcnt lgkmcnt(0)

.LBB0_58:
	s_or_b64 exec, exec, s[26:27]
	s_and_b32 s21, s20, 0xfff
	s_ashr_i32 s20, s20, 9
	v_and_or_b32 v162, s20, -8, v193
	v_ashrrev_i32_e32 v163, 31, v162
	v_lshlrev_b64 v[162:163], 14, v[162:163]
	v_lshl_add_u64 v[162:163], s[22:23], 0, v[162:163]
	s_lshl_b32 s24, s21, 2
	v_lshl_add_u64 v[162:163], v[162:163], 0, s[24:25]
	global_store_dword v[162:163], v161, off sc0 sc1

.LBB0_60:
	s_add_i32 s70, s20, s58
	s_cmp_lt_i32 s70, 0x8000
	s_cselect_b32 s18, s70, s20
	s_ashr_i32 s19, s18, 31
	s_lshl_b64 s[18:19], s[18:19], 12
	v_lshl_add_u64 v[156:157], v[176:177], 0, s[18:19]
	global_load_dwordx4 v[144:147], v[156:157], off nt
	global_load_dwordx4 v[148:151], v[156:157], off offset:1024 nt
	global_load_dwordx4 v[152:155], v[156:157], off offset:2048 nt
	s_nop 0
	global_load_dwordx4 v[156:159], v[156:157], off offset:3072 nt
	s_waitcnt vmcnt(4) lgkmcnt(14)
	v_fma_f32 v183, v172, v16, 0
	v_fmac_f32_e32 v183, v173, v24
	v_fmac_f32_e32 v183, v174, v32
	v_fmac_f32_e32 v183, v175, v40
	v_pk_mul_f32 v[184:185], v[170:171], v[170:171]
	v_pk_mul_f32 v[186:187], v[168:169], v[168:169]
	v_fma_f32 v205, v172, v17, 0
	v_fmac_f32_e32 v183, v168, v48
	v_pk_mov_b32 v[188:189], v[186:187], v[184:185] op_sel:[1,0]
	v_mov_b32_e32 v187, v185
	v_fmac_f32_e32 v205, v173, v25
	v_fmac_f32_e32 v183, v169, v56
	v_pk_add_f32 v[184:185], v[188:189], v[186:187]
	v_fmac_f32_e32 v205, v174, v33
	v_fmac_f32_e32 v183, v170, v64
	v_pk_add_f32 v[184:185], v[184:185], v[184:185] op_sel_hi:[0,1]
	v_fmac_f32_e32 v205, v175, v41
	v_fmac_f32_e32 v183, v171, v72
	v_pk_mul_f32 v[198:199], v[174:175], v[174:175]
	v_pk_mul_f32 v[200:201], v[172:173], v[172:173]
	v_mul_f32_e32 v184, v164, v164
	v_fma_f32 v207, v172, v18, 0
	v_fmac_f32_e32 v205, v168, v49
	v_fmac_f32_e32 v183, v164, v80
	v_pk_mov_b32 v[202:203], v[200:201], v[198:199] op_sel:[1,0]
	v_mov_b32_e32 v201, v199
	v_pk_fma_f32 v[186:187], v[164:165], v[164:165], v[184:185] op_sel_hi:[1,1,0]
	v_mul_f32_e32 v184, v166, v166
	v_fmac_f32_e32 v207, v173, v26
	v_fmac_f32_e32 v205, v169, v57
	s_waitcnt lgkmcnt(13)
	v_fmac_f32_e32 v183, v165, v88
	v_pk_add_f32 v[198:199], v[202:203], v[200:201]
	v_pk_fma_f32 v[190:191], v[166:167], v[166:167], v[184:185] op_sel_hi:[1,1,0]
	v_fmac_f32_e32 v207, v174, v34
	v_fmac_f32_e32 v205, v170, v65
	s_waitcnt lgkmcnt(11)
	v_fmac_f32_e32 v183, v166, v96
	v_pk_add_f32 v[198:199], v[198:199], v[198:199] op_sel_hi:[0,1]
	v_mul_f32_e32 v186, v160, v160
	v_mul_f32_e32 v190, v161, v161
	v_mul_f32_e32 v184, v162, v162
	v_mul_f32_e32 v188, v163, v163
	v_fmac_f32_e32 v207, v175, v42
	v_fmac_f32_e32 v205, v171, v73
	s_waitcnt lgkmcnt(9)
	v_fmac_f32_e32 v183, v167, v104
	v_mov_b32_e32 v189, v199
	v_fma_f32 v209, v172, v19, 0
	v_fmac_f32_e32 v207, v168, v50
	v_fmac_f32_e32 v205, v164, v81
	s_waitcnt lgkmcnt(7)
	v_fmac_f32_e32 v183, v160, v112
	v_pk_add_f32 v[186:187], v[186:187], v[190:191]
	v_pk_add_f32 v[184:185], v[184:185], v[188:189]
	v_fmac_f32_e32 v209, v173, v27
	v_fmac_f32_e32 v207, v169, v58
	v_fmac_f32_e32 v205, v165, v89
	s_waitcnt lgkmcnt(5)
	v_fmac_f32_e32 v183, v161, v120
	v_pk_add_f32 v[184:185], v[186:187], v[184:185]
	v_fmac_f32_e32 v209, v174, v35
	v_fmac_f32_e32 v207, v170, v66
	v_fmac_f32_e32 v205, v166, v97
	s_waitcnt lgkmcnt(3)
	v_fmac_f32_e32 v183, v162, v128
	v_add_f32_e32 v184, v184, v185
	v_fmac_f32_e32 v209, v175, v43
	v_fmac_f32_e32 v207, v171, v74
	v_fmac_f32_e32 v205, v167, v105
	s_waitcnt lgkmcnt(1)
	v_fmac_f32_e32 v183, v163, v136
	v_add_f32_dpp v184, v184, v184 row_ror:8 row_mask:0xf bank_mask:0xf bound_ctrl:1
	v_fma_f32 v204, v172, v20, 0
	v_fmac_f32_e32 v209, v168, v51
	v_fmac_f32_e32 v207, v164, v82
	v_fmac_f32_e32 v205, v160, v113
	v_add_f32_dpp v184, v184, v184 row_ror:4 row_mask:0xf bank_mask:0xf bound_ctrl:1
	v_add_f32_dpp v183, v183, v183 row_ror:8 row_mask:0xf bank_mask:0xf bound_ctrl:1
	v_fmac_f32_e32 v204, v173, v28
	v_fmac_f32_e32 v209, v169, v59
	v_fmac_f32_e32 v207, v165, v90
	v_fmac_f32_e32 v205, v161, v121
	v_add_f32_dpp v184, v184, v184 row_ror:2 row_mask:0xf bank_mask:0xf bound_ctrl:1
	v_add_f32_dpp v183, v183, v183 row_ror:4 row_mask:0xf bank_mask:0xf bound_ctrl:1
	v_fmac_f32_e32 v204, v174, v36
	v_fmac_f32_e32 v209, v170, v67
	v_fmac_f32_e32 v207, v166, v98
	v_fmac_f32_e32 v205, v162, v129
	v_add_f32_dpp v184, v184, v184 row_ror:1 row_mask:0xf bank_mask:0xf bound_ctrl:1
	v_add_f32_dpp v183, v183, v183 row_ror:2 row_mask:0xf bank_mask:0xf bound_ctrl:1
	v_fmac_f32_e32 v204, v175, v44
	v_fmac_f32_e32 v209, v171, v75
	v_fmac_f32_e32 v207, v167, v106
	v_fmac_f32_e32 v205, v163, v137
	v_readlane_b32 s24, v184, 48
	v_add_f32_dpp v183, v183, v183 row_ror:1 row_mask:0xf bank_mask:0xf bound_ctrl:1
	v_fma_f32 v206, v172, v21, 0
	v_fmac_f32_e32 v204, v168, v52
	v_fmac_f32_e32 v209, v164, v83
	v_fmac_f32_e32 v207, v160, v114
	v_mov_b32_e32 v185, s24
	v_readlane_b32 s26, v183, 0
	v_readlane_b32 s24, v183, 16
	v_readlane_b32 s27, v183, 32
	v_readlane_b32 s71, v183, 48
	v_add_f32_dpp v183, v205, v205 row_ror:8 row_mask:0xf bank_mask:0xf bound_ctrl:1
	v_fmac_f32_e32 v206, v173, v29
	v_fmac_f32_e32 v204, v169, v60
	v_fmac_f32_e32 v209, v165, v91
	v_fmac_f32_e32 v207, v161, v122
	v_add_f32_dpp v183, v183, v183 row_ror:4 row_mask:0xf bank_mask:0xf bound_ctrl:1
	v_fmac_f32_e32 v206, v174, v37
	v_fmac_f32_e32 v204, v170, v68
	v_fmac_f32_e32 v209, v166, v99
	v_fmac_f32_e32 v207, v162, v130
	v_add_f32_dpp v183, v183, v183 row_ror:2 row_mask:0xf bank_mask:0xf bound_ctrl:1
	v_fmac_f32_e32 v206, v175, v45
	v_fmac_f32_e32 v204, v171, v76
	v_fmac_f32_e32 v209, v167, v107
	v_fmac_f32_e32 v207, v163, v138
	v_readlane_b32 s21, v184, 16
	v_add_f32_dpp v183, v183, v183 row_ror:1 row_mask:0xf bank_mask:0xf bound_ctrl:1
	v_fma_f32 v208, v172, v22, 0
	v_fmac_f32_e32 v206, v168, v53
	v_fmac_f32_e32 v204, v164, v84
	v_fmac_f32_e32 v209, v160, v115
	v_readlane_b32 s18, v184, 0
	v_readlane_b32 s19, v184, 32
	v_mov_b32_e32 v184, s21
	v_readlane_b32 s28, v183, 0
	v_readlane_b32 s72, v183, 16
	v_readlane_b32 s29, v183, 32
	v_readlane_b32 s73, v183, 48
	v_add_f32_dpp v183, v207, v207 row_ror:8 row_mask:0xf bank_mask:0xf bound_ctrl:1
	v_fmac_f32_e32 v208, v173, v30
	v_fmac_f32_e32 v206, v169, v61
	v_fmac_f32_e32 v204, v165, v92
	v_fmac_f32_e32 v209, v161, v123
	v_pk_add_f32 v[184:185], s[18:19], v[184:185]
	v_add_f32_dpp v183, v183, v183 row_ror:4 row_mask:0xf bank_mask:0xf bound_ctrl:1
	v_fmac_f32_e32 v208, v174, v38
	v_fmac_f32_e32 v206, v170, v69
	v_fmac_f32_e32 v204, v166, v100
	v_fmac_f32_e32 v209, v162, v131
	v_add_f32_e32 v184, v184, v185
	v_add_f32_dpp v183, v183, v183 row_ror:2 row_mask:0xf bank_mask:0xf bound_ctrl:1
	v_fmac_f32_e32 v208, v175, v46
	v_fmac_f32_e32 v206, v171, v77
	v_fmac_f32_e32 v204, v167, v108
	v_fmamk_f32 v184, v184, 0x3a800000, v194
	v_fmac_f32_e32 v209, v163, v139
	v_add_f32_dpp v183, v183, v183 row_ror:1 row_mask:0xf bank_mask:0xf bound_ctrl:1
	v_fma_f32 v210, v172, v23, 0
	v_fmac_f32_e32 v208, v168, v54
	v_fmac_f32_e32 v206, v164, v85
	v_fmac_f32_e32 v204, v160, v116
	v_mul_f32_e32 v185, 0x4f800000, v184
	v_cmp_gt_f32_e32 vcc, s59, v184
	v_readlane_b32 s30, v183, 0
	v_readlane_b32 s79, v183, 16
	v_readlane_b32 s31, v183, 32
	v_readlane_b32 s80, v183, 48
	v_add_f32_dpp v183, v209, v209 row_ror:8 row_mask:0xf bank_mask:0xf bound_ctrl:1
	v_fmac_f32_e32 v210, v173, v31
	v_fmac_f32_e32 v208, v169, v62
	v_fmac_f32_e32 v206, v165, v93
	v_fmac_f32_e32 v204, v161, v124
	v_cndmask_b32_e32 v184, v184, v185, vcc
	v_add_f32_dpp v183, v183, v183 row_ror:4 row_mask:0xf bank_mask:0xf bound_ctrl:1
	v_fmac_f32_e32 v210, v174, v39
	v_fmac_f32_e32 v208, v170, v70
	v_fmac_f32_e32 v206, v166, v101
	v_fmac_f32_e32 v204, v162, v132
	v_sqrt_f32_e32 v185, v184
	v_add_f32_dpp v183, v183, v183 row_ror:2 row_mask:0xf bank_mask:0xf bound_ctrl:1
	v_fmac_f32_e32 v210, v175, v47
	v_fmac_f32_e32 v208, v171, v78
	v_fmac_f32_e32 v206, v167, v109
	s_waitcnt lgkmcnt(0)
	v_fmac_f32_e32 v204, v163, v140
	v_add_f32_dpp v183, v183, v183 row_ror:1 row_mask:0xf bank_mask:0xf bound_ctrl:1
	v_fmac_f32_e32 v210, v168, v55
	v_fmac_f32_e32 v208, v164, v86
	v_fmac_f32_e32 v206, v160, v117
	v_readlane_b32 s40, v183, 0
	v_readlane_b32 s81, v183, 16
	v_readlane_b32 s41, v183, 32
	v_readlane_b32 s82, v183, 48
	v_add_f32_dpp v183, v204, v204 row_ror:8 row_mask:0xf bank_mask:0xf bound_ctrl:1
	v_fmac_f32_e32 v210, v169, v63
	v_fmac_f32_e32 v208, v165, v94
	v_fmac_f32_e32 v206, v161, v125
	v_add_f32_dpp v183, v183, v183 row_ror:4 row_mask:0xf bank_mask:0xf bound_ctrl:1
	v_fmac_f32_e32 v210, v170, v71
	v_fmac_f32_e32 v208, v166, v102
	v_fmac_f32_e32 v206, v162, v133
	v_add_u32_e32 v186, -1, v185
	v_add_f32_dpp v183, v183, v183 row_ror:2 row_mask:0xf bank_mask:0xf bound_ctrl:1
	v_fmac_f32_e32 v210, v171, v79
	v_fmac_f32_e32 v208, v167, v110
	v_fmac_f32_e32 v206, v163, v141
	v_fma_f32 v187, -v186, v185, v184
	v_add_f32_dpp v183, v183, v183 row_ror:1 row_mask:0xf bank_mask:0xf bound_ctrl:1
	v_fmac_f32_e32 v210, v164, v87
	v_fmac_f32_e32 v208, v160, v118
	v_cmp_ge_f32_e64 s[18:19], 0, v187
	v_add_u32_e32 v187, 1, v185
	v_readlane_b32 s42, v183, 0
	v_readlane_b32 s83, v183, 16
	v_readlane_b32 s43, v183, 32
	v_readlane_b32 s84, v183, 48
	v_add_f32_dpp v183, v206, v206 row_ror:8 row_mask:0xf bank_mask:0xf bound_ctrl:1
	v_fmac_f32_e32 v210, v165, v95
	v_fmac_f32_e32 v208, v161, v126
	v_cndmask_b32_e64 v186, v185, v186, s[18:19]
	v_fma_f32 v185, -v187, v185, v184
	v_add_f32_dpp v183, v183, v183 row_ror:4 row_mask:0xf bank_mask:0xf bound_ctrl:1
	v_fmac_f32_e32 v210, v166, v103
	v_fmac_f32_e32 v208, v162, v134
	v_cmp_lt_f32_e64 s[18:19], 0, v185
	v_add_f32_dpp v183, v183, v183 row_ror:2 row_mask:0xf bank_mask:0xf bound_ctrl:1
	v_fmac_f32_e32 v210, v167, v111
	v_fmac_f32_e32 v208, v163, v142
	v_cndmask_b32_e64 v185, v186, v187, s[18:19]
	v_add_f32_dpp v183, v183, v183 row_ror:1 row_mask:0xf bank_mask:0xf bound_ctrl:1
	v_fmac_f32_e32 v210, v160, v119
	v_mul_f32_e32 v186, 0x37800000, v185
	v_readlane_b32 s48, v183, 0
	v_readlane_b32 s85, v183, 16
	v_readlane_b32 s49, v183, 32
	v_readlane_b32 s86, v183, 48
	v_add_f32_dpp v183, v208, v208 row_ror:8 row_mask:0xf bank_mask:0xf bound_ctrl:1
	v_fmac_f32_e32 v210, v161, v127
	v_cndmask_b32_e32 v185, v185, v186, vcc
	v_cmp_class_f32_e32 vcc, v184, v195
	v_add_f32_dpp v183, v183, v183 row_ror:4 row_mask:0xf bank_mask:0xf bound_ctrl:1
	v_fmac_f32_e32 v210, v162, v135
	v_cndmask_b32_e32 v184, v185, v184, vcc
	v_add_f32_dpp v183, v183, v183 row_ror:2 row_mask:0xf bank_mask:0xf bound_ctrl:1
	v_fmac_f32_e32 v210, v163, v143
	v_div_scale_f32 v185, s[18:19], v184, v184, 1.0
	v_add_f32_dpp v183, v183, v183 row_ror:1 row_mask:0xf bank_mask:0xf bound_ctrl:1
	v_rcp_f32_e32 v186, v185
	v_readlane_b32 s54, v183, 0
	v_readlane_b32 s87, v183, 16
	v_readlane_b32 s55, v183, 32
	v_readlane_b32 s88, v183, 48
	v_add_f32_dpp v183, v210, v210 row_ror:8 row_mask:0xf bank_mask:0xf bound_ctrl:1
	s_ashr_i32 s21, s20, 31
	s_lshl_b64 s[18:19], s[20:21], 11
	v_add_f32_dpp v183, v183, v183 row_ror:4 row_mask:0xf bank_mask:0xf bound_ctrl:1
	s_nop 1
	v_add_f32_dpp v183, v183, v183 row_ror:2 row_mask:0xf bank_mask:0xf bound_ctrl:1
	s_nop 1
	v_add_f32_dpp v183, v183, v183 row_ror:1 row_mask:0xf bank_mask:0xf bound_ctrl:1
	s_nop 0
	v_readlane_b32 s56, v183, 0
	v_readlane_b32 s89, v183, 16
	v_readlane_b32 s57, v183, 32
	v_readlane_b32 s90, v183, 48
	v_fma_f32 v183, -v185, v186, 1.0
	v_fmac_f32_e32 v186, v183, v186
	v_div_scale_f32 v183, vcc, 1.0, v184, 1.0
	v_mul_f32_e32 v187, v183, v186
	v_fma_f32 v188, -v185, v187, v183
	v_fmac_f32_e32 v187, v188, v186
	v_fma_f32 v183, -v185, v187, v183
	v_div_fmas_f32 v183, v183, v186, v187
	v_div_fixup_f32 v184, v183, v184, 1.0
	v_pk_mul_f32 v[172:173], v[172:173], v[184:185] op_sel_hi:[1,0]
	v_pk_mul_f32 v[174:175], v[174:175], v[184:185] op_sel_hi:[1,0]
	v_pk_mul_f32 v[168:169], v[168:169], v[184:185] op_sel_hi:[1,0]
	v_pk_mul_f32 v[170:171], v[170:171], v[184:185] op_sel_hi:[1,0]
	v_pk_mul_f32 v[164:165], v[164:165], v[184:185] op_sel_hi:[1,0]
	v_pk_mul_f32 v[166:167], v[166:167], v[184:185] op_sel_hi:[1,0]
	v_pk_mul_f32 v[160:161], v[160:161], v[184:185] op_sel_hi:[1,0]
	v_pk_mul_f32 v[162:163], v[162:163], v[184:185] op_sel_hi:[1,0]
	v_lshl_add_u64 v[186:187], v[178:179], 0, s[18:19]
	v_cvt_pk_bf16_f32 v172, v172, v173
	v_cvt_pk_bf16_f32 v173, v174, v175
	v_cvt_pk_bf16_f32 v168, v168, v169
	v_cvt_pk_bf16_f32 v169, v170, v171
	v_cvt_pk_bf16_f32 v164, v164, v165
	v_cvt_pk_bf16_f32 v165, v166, v167
	v_cvt_pk_bf16_f32 v160, v160, v161
	v_cvt_pk_bf16_f32 v161, v162, v163
	global_store_dwordx2 v[186:187], v[172:173], off sc0 sc1
	global_store_dwordx2 v[186:187], v[168:169], off offset:512 sc0 sc1
	global_store_dwordx2 v[186:187], v[164:165], off offset:1024 sc0 sc1
	global_store_dwordx2 v[186:187], v[160:161], off offset:1536 sc0 sc1
	s_and_saveexec_b64 s[18:19], s[0:1]
	s_cbranch_execz .LBB0_59
	global_load_dword v160, v[180:181], off
	v_mov_b32_e32 v162, s89
	v_mov_b32_e32 v163, s90
	v_pk_add_f32 v[162:163], s[56:57], v[162:163]
	s_nop 0
	v_add_f32_e32 v161, v162, v163
	v_mov_b32_e32 v162, s87
	v_mov_b32_e32 v163, s88
	v_pk_add_f32 v[162:163], s[54:55], v[162:163]
	s_nop 0
	v_add_f32_e32 v164, v162, v163
	v_mov_b32_e32 v162, s85
	v_mov_b32_e32 v163, s86
	v_pk_add_f32 v[162:163], s[48:49], v[162:163]
	s_nop 0
	v_add_f32_e32 v165, v162, v163
	v_mov_b32_e32 v162, s83
	v_mov_b32_e32 v163, s84
	v_pk_add_f32 v[162:163], s[42:43], v[162:163]
	s_nop 0
	v_add_f32_e32 v166, v162, v163
	v_mov_b32_e32 v162, s81
	v_mov_b32_e32 v163, s82
	v_pk_add_f32 v[162:163], s[40:41], v[162:163]
	s_nop 0
	v_add_f32_e32 v167, v162, v163
	v_mov_b32_e32 v162, s79
	v_mov_b32_e32 v163, s80
	v_pk_add_f32 v[162:163], s[30:31], v[162:163]
	s_nop 0
	v_add_f32_e32 v168, v162, v163
	v_mov_b32_e32 v162, s72
	v_mov_b32_e32 v163, s73
	v_pk_add_f32 v[162:163], s[28:29], v[162:163]
	s_nop 0
	v_add_f32_e32 v169, v162, v163
	v_mov_b32_e32 v162, s24
	v_mov_b32_e32 v163, s71
	v_pk_add_f32 v[162:163], s[26:27], v[162:163]
	s_nop 0
	v_add_f32_e32 v162, v162, v163
	v_cndmask_b32_e64 v162, v162, v169, s[16:17]
	v_cndmask_b32_e64 v162, v162, v168, s[4:5]
	v_cndmask_b32_e64 v162, v162, v167, s[6:7]
	v_cndmask_b32_e64 v162, v162, v166, s[8:9]
	v_cndmask_b32_e64 v162, v162, v165, s[10:11]
	v_cndmask_b32_e64 v162, v162, v164, s[12:13]
	v_cndmask_b32_e64 v161, v162, v161, s[14:15]
	s_waitcnt vmcnt(0)
	v_fmac_f32_e32 v160, v184, v161
	v_cmp_ngt_f32_e32 vcc, 0, v160
	s_and_saveexec_b64 s[26:27], vcc
	s_xor_b64 s[26:27], exec, s[26:27]
	s_cbranch_execz .LBB0_63
	v_mul_f32_e32 v161, 0xbfb8aa3b, v160
	v_rndne_f32_e32 v162, v161
	v_sub_f32_e32 v163, v161, v162
	v_fma_f32 v161, v160, s60, -v161
	v_fmac_f32_e32 v161, 0xb2a5705f, v160
	v_add_f32_e32 v161, v163, v161
	v_cvt_i32_f32_e32 v162, v162
	v_exp_f32_e32 v161, v161
	v_cmp_nlt_f32_e32 vcc, s61, v160
	v_ldexp_f32 v161, v161, v162
	s_nop 0
	v_cndmask_b32_e32 v161, 0, v161, vcc
	v_cmp_ngt_f32_e32 vcc, s62, v160
	s_nop 1
	v_cndmask_b32_e32 v174, v197, v161, vcc
	v_add_f32_e32 v162, 1.0, v174
	v_add_f32_e32 v160, -1.0, v162
	v_sub_f32_e32 v161, v160, v162
	v_add_f32_e32 v161, 1.0, v161
	v_sub_f32_e32 v160, v174, v160
	v_add_f32_e32 v163, v160, v161
	v_frexp_mant_f32_e32 v164, v162
	v_cvt_f64_f32_e32 v[160:161], v162
	v_frexp_exp_i32_f64_e32 v160, v[160:161]
	v_cmp_gt_f32_e32 vcc, s64, v164
	s_nop 1
	v_subbrev_co_u32_e32 v168, vcc, 0, v160, vcc
	v_sub_u32_e32 v160, 0, v168
	v_ldexp_f32 v161, v162, v160
	v_add_f32_e32 v162, -1.0, v161
	v_add_f32_e32 v164, 1.0, v161
	v_ldexp_f32 v160, v163, v160
	v_add_f32_e32 v163, 1.0, v162
	v_add_f32_e32 v165, -1.0, v164
	v_sub_f32_e32 v163, v161, v163
	v_sub_f32_e32 v161, v161, v165
	v_add_f32_e32 v163, v160, v163
	v_add_f32_e32 v160, v160, v161
	v_add_f32_e32 v169, v164, v160
	v_rcp_f32_e32 v171, v169
	v_sub_f32_e32 v161, v164, v169
	v_add_f32_e32 v170, v160, v161
	v_add_f32_e32 v161, v162, v163
	v_mul_f32_e32 v173, v161, v171
	v_sub_f32_e32 v160, v162, v161
	v_mul_f32_e32 v162, v169, v173
	v_fma_f32 v164, v173, v169, -v162
	v_fmac_f32_e32 v164, v173, v170
	v_add_f32_e32 v172, v163, v160
	v_add_f32_e32 v160, v162, v164
	v_sub_f32_e32 v163, v161, v160
	v_pk_add_f32 v[166:167], v[160:161], v[162:163] neg_lo:[0,1] neg_hi:[0,1]
	v_mov_b32_e32 v165, v160
	v_pk_add_f32 v[160:161], v[166:167], v[164:165] neg_lo:[0,1] neg_hi:[0,1]
	v_cmp_neq_f32_e32 vcc, s63, v174
	v_add_f32_e32 v161, v172, v161
	v_add_f32_e32 v160, v160, v161
	v_add_f32_e32 v161, v163, v160
	v_mul_f32_e32 v172, v171, v161
	v_mul_f32_e32 v162, v169, v172
	v_fma_f32 v164, v172, v169, -v162
	v_fmac_f32_e32 v164, v172, v170
	v_sub_f32_e32 v163, v163, v161
	v_add_f32_e32 v169, v160, v163
	v_add_f32_e32 v160, v162, v164
	v_sub_f32_e32 v163, v161, v160
	v_pk_add_f32 v[166:167], v[160:161], v[162:163] neg_lo:[0,1] neg_hi:[0,1]
	v_mov_b32_e32 v165, v160
	v_pk_add_f32 v[160:161], v[166:167], v[164:165] neg_lo:[0,1] neg_hi:[0,1]
	s_nop 0
	v_add_f32_e32 v161, v169, v161
	v_add_f32_e32 v160, v160, v161
	v_add_f32_e32 v161, v173, v172
	v_add_f32_e32 v160, v163, v160
	v_sub_f32_e32 v162, v161, v173
	v_mul_f32_e32 v160, v171, v160
	v_sub_f32_e32 v162, v172, v162
	v_add_f32_e32 v162, v162, v160
	v_add_f32_e32 v164, v161, v162
	v_mul_f32_e32 v165, v164, v164
	v_fmamk_f32 v160, v165, 0x3e9b6dac, v196
	v_fmaak_f32 v183, v165, v160, 0x3f2aaada
	v_cvt_f32_i32_e32 v160, v168
	v_sub_f32_e32 v161, v164, v161
	v_sub_f32_e32 v161, v162, v161
	v_ldexp_f32 v166, v161, 1
	v_mul_f32_e32 v161, v164, v165
	v_ldexp_f32 v163, v164, 1
	v_pk_mul_f32 v[164:165], v[160:161], v[182:183]
	s_nop 0
	v_fma_f32 v162, v160, s65, -v164
	v_fmac_f32_e32 v162, 0xb102e308, v160
	v_pk_add_f32 v[160:161], v[164:165], v[162:163]
	s_nop 0
	v_sub_f32_e32 v163, v161, v163
	v_sub_f32_e32 v163, v165, v163
	v_add_f32_e32 v167, v166, v163
	v_mov_b32_e32 v166, v164
	v_pk_add_f32 v[164:165], v[160:161], v[164:165] neg_lo:[0,1] neg_hi:[0,1]
	v_pk_add_f32 v[168:169], v[160:161], v[166:167]
	v_mov_b32_e32 v163, v160
	v_mov_b32_e32 v165, v169
	v_pk_add_f32 v[170:171], v[162:163], v[164:165] neg_lo:[0,1] neg_hi:[0,1]
	v_pk_add_f32 v[162:163], v[162:163], v[164:165]
	v_mov_b32_e32 v166, v167
	v_pk_add_f32 v[164:165], v[162:163], v[160:161] op_sel:[1,0] op_sel_hi:[0,1] neg_lo:[0,1] neg_hi:[0,1]
	v_pk_add_f32 v[172:173], v[168:169], v[164:165] op_sel_hi:[1,0] neg_lo:[0,1] neg_hi:[0,1]
	v_mov_b32_e32 v168, v169
	v_mov_b32_e32 v169, v163
	v_pk_mov_b32 v[164:165], v[160:161], v[164:165] op_sel:[1,0]
	v_mov_b32_e32 v167, v160
	v_pk_add_f32 v[164:165], v[168:169], v[164:165] neg_lo:[0,1] neg_hi:[0,1]
	v_mov_b32_e32 v172, v170
	v_pk_add_f32 v[160:161], v[166:167], v[164:165] neg_lo:[0,1] neg_hi:[0,1]
	v_mov_b32_e32 v171, v163
	v_pk_add_f32 v[164:165], v[172:173], v[160:161]
	s_nop 0
	v_pk_add_f32 v[166:167], v[164:165], v[164:165] op_sel:[0,1] op_sel_hi:[1,0]
	s_nop 0
	v_pk_add_f32 v[162:163], v[162:163], v[166:167] op_sel:[1,0] op_sel_hi:[0,1]
	v_mov_b32_e32 v165, v162
	v_pk_add_f32 v[168:169], v[164:165], v[170:171] neg_lo:[0,1] neg_hi:[0,1]
	v_mov_b32_e32 v161, v166
	v_sub_f32_e32 v163, v164, v168
	v_pk_add_f32 v[160:161], v[160:161], v[168:169] neg_lo:[0,1] neg_hi:[0,1]
	v_sub_f32_e32 v163, v170, v163
	v_add_f32_e32 v160, v160, v163
	v_add_f32_e32 v160, v160, v161
	v_add_f32_e32 v160, v162, v160
	v_cndmask_b32_e32 v160, v197, v160, vcc
	v_cmp_lt_f32_e64 vcc, |v174|, s66
	s_nop 1
	v_cndmask_b32_e32 v160, v160, v174, vcc
	v_xor_b32_e32 v161, 0x80000000, v160

.LBB0_68:
	global_load_dwordx4 v[8:11], v[4:5], off offset:-16 nt
	global_load_dwordx4 v[12:15], v[4:5], off nt
	v_add_u32_e32 v7, -1, v7
	v_cmp_eq_u32_e32 vcc, 0, v7
	v_add_u32_e32 v0, s6, v0
	v_lshl_add_u64 v[4:5], v[4:5], 0, s[12:13]
	s_or_b64 s[10:11], vcc, s[10:11]
	s_waitcnt vmcnt(1)
	v_cvt_pk_bf16_f32 v8, v8, v9
	v_cvt_pk_bf16_f32 v9, v10, v11
	s_waitcnt vmcnt(0)
	v_cvt_pk_bf16_f32 v10, v12, v13
	v_cvt_pk_bf16_f32 v11, v14, v15
	global_store_dwordx4 v[2:3], v[8:11], off sc0 sc1
	v_lshl_add_u64 v[2:3], v[2:3], 0, s[8:9]
	s_andn2_b64 exec, exec, s[10:11]
	s_cbranch_execnz .LBB0_68
	s_or_b64 exec, exec, s[10:11]

.LBB0_72:
	v_ashrrev_i32_e32 v1, 31, v0
	v_lshlrev_b64 v[2:3], 5, v[0:1]
	v_lshl_add_u64 v[10:11], s[38:39], 0, v[2:3]
	global_load_dwordx4 v[2:5], v[10:11], off nt
	global_load_dwordx4 v[6:9], v[10:11], off offset:16 nt
	v_add_u32_e32 v10, s6, v0
	v_ashrrev_i32_e32 v11, 31, v10
	v_lshl_add_u64 v[12:13], v[0:1], 4, s[0:1]
	v_lshlrev_b64 v[14:15], 5, v[10:11]
	v_lshl_add_u64 v[14:15], s[38:39], 0, v[14:15]
	s_waitcnt vmcnt(1)
	v_cvt_pk_bf16_f32 v2, v2, v3
	v_cvt_pk_bf16_f32 v3, v4, v5
	s_waitcnt vmcnt(0)
	v_cvt_pk_bf16_f32 v4, v6, v7
	v_cvt_pk_bf16_f32 v5, v8, v9
	global_store_dwordx4 v[12:13], v[2:5], off sc0 sc1
	global_load_dwordx4 v[2:5], v[14:15], off nt
	s_nop 0
	global_load_dwordx4 v[6:9], v[14:15], off offset:16 nt
	v_add_u32_e32 v12, s10, v0
	v_ashrrev_i32_e32 v13, 31, v12
	v_lshl_add_u64 v[14:15], v[10:11], 4, s[0:1]
	v_lshlrev_b64 v[16:17], 5, v[12:13]
	v_lshl_add_u64 v[16:17], s[38:39], 0, v[16:17]
	v_lshl_add_u64 v[12:13], v[12:13], 4, s[0:1]
	s_waitcnt vmcnt(1)
	v_cvt_pk_bf16_f32 v2, v2, v3
	v_cvt_pk_bf16_f32 v3, v4, v5
	s_waitcnt vmcnt(0)
	v_cvt_pk_bf16_f32 v4, v6, v7
	v_cvt_pk_bf16_f32 v5, v8, v9
	global_store_dwordx4 v[14:15], v[2:5], off sc0 sc1
	global_load_dwordx4 v[2:5], v[16:17], off nt
	s_nop 0
	global_load_dwordx4 v[6:9], v[16:17], off offset:16 nt
	v_add_u32_e32 v14, s7, v0
	v_ashrrev_i32_e32 v15, 31, v14
	v_lshlrev_b64 v[0:1], 5, v[14:15]
	v_lshl_add_u64 v[16:17], s[38:39], 0, v[0:1]
	s_waitcnt vmcnt(1)
	v_cvt_pk_bf16_f32 v0, v2, v3
	v_cvt_pk_bf16_f32 v1, v4, v5
	s_waitcnt vmcnt(0)
	v_cvt_pk_bf16_f32 v2, v6, v7
	v_cvt_pk_bf16_f32 v3, v8, v9
	global_store_dwordx4 v[12:13], v[0:3], off sc0 sc1
	global_load_dwordx4 v[2:5], v[16:17], off nt
	s_nop 0
	global_load_dwordx4 v[6:9], v[16:17], off offset:16 nt
	v_add_u32_e32 v0, s11, v10
	v_cmp_lt_i32_e32 vcc, s12, v0
	v_lshl_add_u64 v[10:11], v[14:15], 4, s[0:1]
	s_or_b64 s[8:9], vcc, s[8:9]
	s_waitcnt vmcnt(1)
	v_cvt_pk_bf16_f32 v2, v2, v3
	v_cvt_pk_bf16_f32 v3, v4, v5
	s_waitcnt vmcnt(0)
	v_cvt_pk_bf16_f32 v4, v6, v7
	v_cvt_pk_bf16_f32 v5, v8, v9
	global_store_dwordx4 v[10:11], v[2:5], off sc0 sc1
	s_andn2_b64 exec, exec, s[8:9]
	s_cbranch_execnz .LBB0_72

.LBB0_105:
	s_andn2_saveexec_b64 s[6:7], s[6:7]
	s_cbranch_execz .LBB0_125
	s_mov_b64 s[6:7], exec
	s_nop 0
	s_waitcnt lgkmcnt(0)
	s_waitcnt vmcnt(0)
	v_mbcnt_lo_u32_b32 v1, s6, 0
	v_mbcnt_hi_u32_b32 v1, s7, v1
	v_cmp_eq_u32_e32 vcc, 0, v1
	s_and_saveexec_b64 s[8:9], vcc
	s_cbranch_execz .LBB0_108
	s_bcnt1_i32_b64 s6, s[6:7]
	v_mov_b32_e32 v2, 0xb000
	v_mov_b32_e32 v3, s6
	global_atomic_add v2, v2, v3, s[76:77] offset:1024 sc0
